# GEMM mainloops: the redundant second lgkmcnt(0) after each sub-phase barrier removed (16 sites), on top of the leaner up-GEMM epilogue
# speedup vs baseline: 1.0053x; 1.0043x over previous
; #define PG8_STAGE(bufoff, gbase, voff) do { _Pragma("unroll") for (int _i = 0; _i < 2; ++_i) \
;         __builtin_amdgcn_global_load_lds((const unsigned*)((const char*)(gbase) + (voff)[_i]), (PG8_LAS unsigned*)(lds + (bufoff) + ldsw + _i * 8192), 16, 0, 0); } while (0)
; #define PG8_LDA(dst, b, h) do { _Pragma("unroll") for (int m = 0; m < 4; ++m) _Pragma("unroll") for (int k = 0; k < 2; ++k) dst[m][k] = *(const PG8_LAS bf16x8*)(lds + PG8_SA(b, h) + aoff + m * 2048 + k * 1024); } while (0)
; #define PG8_LDB(dst, b, h) do { _Pragma("unroll") for (int n = 0; n < 2; ++n) _Pragma("unroll") for (int k = 0; k < 2; ++k) dst[n][k] = *(const PG8_LAS bf16x8*)(lds + PG8_SB(b, h) + boff + n * 2048 + k * 1024); } while (0)
; #define PG8_MMA(ai, bj, At, Bt) do { __builtin_amdgcn_s_setprio(1); _Pragma("unroll") for (int m = 0; m < 4; ++m) _Pragma("unroll") for (int n = 0; n < 2; ++n) _Pragma("unroll") for (int k = 0; k < 2; ++k) \
;         acc[ai][bj][m][n] = __builtin_amdgcn_mfma_f32_16x16x32_bf16(Bt[n][k], At[m][k], acc[ai][bj][m][n], 0, 0, 0); __builtin_amdgcn_s_setprio(0); } while (0)
; #define PG8_WAIT_V(n) asm volatile("s_waitcnt vmcnt(" #n ")" ::: "memory")
; #define PG8_WAIT_L(n) asm volatile("s_waitcnt lgkmcnt(" #n ")" ::: "memory")
; #define PG8_BAR __builtin_amdgcn_s_barrier()
; #define PG8_SCHED __builtin_amdgcn_sched_barrier(0)
; template <class Epi, class Sched, bool ALIGN_EPI = false, bool SP2 = false>
; __device__ __forceinline__ void gemm_phase(PG8_LAS unsigned char* lds, const Gemm g, const Sched& S, const Epi& E) {
;     ...
;             PG8_LDB(B0, 0, 0); PG8_LDB(B1, 0, 1); PG8_SCHED; PG8_LDA(At, 0, 0); PG8_STAGE(PG8_SA(1, 1), a1 + hstep, voffA);
;             PG8_WAIT_V(8); PG8_WAIT_L(0); PG8_BAR; PG8_MMA(0, 0, At, B0); PG8_MMA(0, 1, At, B1); PG8_BAR; PG8_SCHED;
;             PG8_LDA(At, 0, 1); PG8_STAGE(PG8_SB(0, 0), b2, voffB); PG8_STAGE(PG8_SB(0, 1), b2 + hstep, voffB); PG8_STAGE(PG8_SA(0, 0), a2, voffA);
;             PG8_WAIT_V(8); PG8_WAIT_L(0); PG8_BAR; PG8_MMA(1, 0, At, B0); PG8_MMA(1, 1, At, B1); PG8_BAR; PG8_SCHED;
.LBB0_67:
	ds_read_b128 v[144:147], v155
	ds_read_b128 v[158:161], v155 offset:1024
	ds_read_b128 v[162:165], v155 offset:2048
	ds_read_b128 v[166:169], v155 offset:3072
	ds_read_b128 v[170:173], v156
	ds_read_b128 v[174:177], v156 offset:1024
	ds_read_b128 v[178:181], v156 offset:2048
	ds_read_b128 v[182:185], v156 offset:3072
	s_add_u32 s26, s24, 0xfffc0080
	s_addc_u32 s27, s25, -1
	s_cmp_eq_u32 s50, 12
	s_cselect_b32 s29, s15, s27
	s_cselect_b32 s28, s46, s26
	s_cselect_b32 s27, s13, s49
	s_cselect_b32 s26, s47, s48
	v_lshl_add_u64 v[218:219], s[24:25], 0, v[136:137]
	s_add_i32 m0, s23, 0xc000
	ds_read_b128 v[186:189], v157
	ds_read_b128 v[190:193], v157 offset:1024
	ds_read_b128 v[194:197], v157 offset:2048
	ds_read_b128 v[198:201], v157 offset:3072
	ds_read_b128 v[202:205], v157 offset:4096
	ds_read_b128 v[206:209], v157 offset:5120
	ds_read_b128 v[210:213], v157 offset:6144
	ds_read_b128 v[214:217], v157 offset:7168
	global_load_lds_dwordx4 v[218:219], off
	v_lshl_add_u64 v[218:219], s[24:25], 0, v[138:139]
	s_add_i32 m0, s23, 0xe000
	s_nop 0
	global_load_lds_dwordx4 v[218:219], off
	s_waitcnt vmcnt(8)
	s_waitcnt lgkmcnt(0)
	s_barrier
	s_setprio 1
	v_mfma_f32_16x16x32_bf16 v[124:127], v[144:147], v[186:189], v[124:127]
	v_mfma_f32_16x16x32_bf16 v[120:123], v[162:165], v[186:189], v[120:123]
	v_mfma_f32_16x16x32_bf16 v[116:119], v[144:147], v[194:197], v[116:119]
	v_mfma_f32_16x16x32_bf16 v[112:115], v[162:165], v[194:197], v[112:115]
	v_mfma_f32_16x16x32_bf16 v[104:107], v[144:147], v[202:205], v[104:107]
	v_mfma_f32_16x16x32_bf16 v[96:99], v[162:165], v[202:205], v[96:99]
	v_mfma_f32_16x16x32_bf16 v[76:79], v[144:147], v[210:213], v[76:79]
	v_mfma_f32_16x16x32_bf16 v[72:75], v[162:165], v[210:213], v[72:75]
	v_mfma_f32_16x16x32_bf16 v[124:127], v[158:161], v[190:193], v[124:127]
	v_mfma_f32_16x16x32_bf16 v[120:123], v[166:169], v[190:193], v[120:123]
	v_mfma_f32_16x16x32_bf16 v[116:119], v[158:161], v[198:201], v[116:119]
	v_mfma_f32_16x16x32_bf16 v[112:115], v[166:169], v[198:201], v[112:115]
	v_mfma_f32_16x16x32_bf16 v[104:107], v[158:161], v[206:209], v[104:107]
	v_mfma_f32_16x16x32_bf16 v[96:99], v[166:169], v[206:209], v[96:99]
	v_mfma_f32_16x16x32_bf16 v[76:79], v[158:161], v[214:217], v[76:79]
	v_mfma_f32_16x16x32_bf16 v[72:75], v[166:169], v[214:217], v[72:75]
	s_setprio 0
	s_setprio 1
	v_mfma_f32_16x16x32_bf16 v[108:111], v[170:173], v[186:189], v[108:111]
	v_mfma_f32_16x16x32_bf16 v[100:103], v[178:181], v[186:189], v[100:103]
	v_mfma_f32_16x16x32_bf16 v[92:95], v[170:173], v[194:197], v[92:95]
	v_mfma_f32_16x16x32_bf16 v[88:91], v[178:181], v[194:197], v[88:91]
	v_mfma_f32_16x16x32_bf16 v[84:87], v[170:173], v[202:205], v[84:87]
	v_mfma_f32_16x16x32_bf16 v[80:83], v[178:181], v[202:205], v[80:83]
	v_mfma_f32_16x16x32_bf16 v[68:71], v[170:173], v[210:213], v[68:71]
	v_mfma_f32_16x16x32_bf16 v[64:67], v[178:181], v[210:213], v[64:67]
	v_mfma_f32_16x16x32_bf16 v[108:111], v[174:177], v[190:193], v[108:111]
	v_mfma_f32_16x16x32_bf16 v[100:103], v[182:185], v[190:193], v[100:103]
	v_mfma_f32_16x16x32_bf16 v[92:95], v[174:177], v[198:201], v[92:95]
	v_mfma_f32_16x16x32_bf16 v[88:91], v[182:185], v[198:201], v[88:91]
	v_mfma_f32_16x16x32_bf16 v[84:87], v[174:177], v[206:209], v[84:87]
	v_mfma_f32_16x16x32_bf16 v[80:83], v[182:185], v[206:209], v[80:83]
	v_mfma_f32_16x16x32_bf16 v[68:71], v[174:177], v[214:217], v[68:71]
	v_mfma_f32_16x16x32_bf16 v[64:67], v[182:185], v[214:217], v[64:67]
	s_setprio 0
	s_barrier
	s_add_i32 s51, s42, s30
	v_lshl_add_u64 v[218:219], s[26:27], 0, v[132:133]
	s_mov_b32 m0, s51
	ds_read_b128 v[186:189], v157 offset:16384
	ds_read_b128 v[190:193], v157 offset:17408
	ds_read_b128 v[194:197], v157 offset:18432
	ds_read_b128 v[198:201], v157 offset:19456
	ds_read_b128 v[202:205], v157 offset:20480
	ds_read_b128 v[206:209], v157 offset:21504
	ds_read_b128 v[210:213], v157 offset:22528
	ds_read_b128 v[214:217], v157 offset:23552
	global_load_lds_dwordx4 v[218:219], off
	s_add_i32 m0, s51, 0x2000
	s_add_u32 s52, s26, 0x40000
	v_lshl_add_u64 v[220:221], s[26:27], 0, v[128:129]
	s_addc_u32 s53, s27, 0
	s_add_i32 s51, s43, s30
	global_load_lds_dwordx4 v[220:221], off
	v_lshl_add_u64 v[222:223], s[52:53], 0, v[132:133]
	s_mov_b32 m0, s51
	v_lshl_add_u64 v[224:225], s[28:29], 0, v[130:131]
	global_load_lds_dwordx4 v[222:223], off
	v_lshl_add_u64 v[222:223], s[52:53], 0, v[128:129]
	s_add_i32 m0, s51, 0x2000
	s_nop 0
	global_load_lds_dwordx4 v[222:223], off
	v_lshl_add_u64 v[222:223], s[28:29], 0, v[134:135]
	s_mov_b32 m0, s23
	s_nop 0
	global_load_lds_dwordx4 v[222:223], off
	s_mov_b32 m0, s34
	s_nop 0
	global_load_lds_dwordx4 v[224:225], off
	s_waitcnt vmcnt(8)
	s_waitcnt lgkmcnt(0)
	s_barrier
; #define PG8_STAGE(bufoff, gbase, voff) do { _Pragma("unroll") for (int _i = 0; _i < 2; ++_i) \
;         __builtin_amdgcn_global_load_lds((const unsigned*)((const char*)(gbase) + (voff)[_i]), (PG8_LAS unsigned*)(lds + (bufoff) + ldsw + _i * 8192), 16, 0, 0); } while (0)
; #define PG8_LDA(dst, b, h) do { _Pragma("unroll") for (int m = 0; m < 4; ++m) _Pragma("unroll") for (int k = 0; k < 2; ++k) dst[m][k] = *(const PG8_LAS bf16x8*)(lds + PG8_SA(b, h) + aoff + m * 2048 + k * 1024); } while (0)
; #define PG8_LDB(dst, b, h) do { _Pragma("unroll") for (int n = 0; n < 2; ++n) _Pragma("unroll") for (int k = 0; k < 2; ++k) dst[n][k] = *(const PG8_LAS bf16x8*)(lds + PG8_SB(b, h) + boff + n * 2048 + k * 1024); } while (0)
; #define PG8_MMA(ai, bj, At, Bt) do { __builtin_amdgcn_s_setprio(1); _Pragma("unroll") for (int m = 0; m < 4; ++m) _Pragma("unroll") for (int n = 0; n < 2; ++n) _Pragma("unroll") for (int k = 0; k < 2; ++k) \
;         acc[ai][bj][m][n] = __builtin_amdgcn_mfma_f32_16x16x32_bf16(Bt[n][k], At[m][k], acc[ai][bj][m][n], 0, 0, 0); __builtin_amdgcn_s_setprio(0); } while (0)
; #define PG8_WAIT_V(n) asm volatile("s_waitcnt vmcnt(" #n ")" ::: "memory")
; #define PG8_WAIT_L(n) asm volatile("s_waitcnt lgkmcnt(" #n ")" ::: "memory")
; #define PG8_BAR __builtin_amdgcn_s_barrier()
; #define PG8_SCHED __builtin_amdgcn_sched_barrier(0)
; template <class Epi, class Sched, bool ALIGN_EPI = false, bool SP2 = false>
; __device__ __forceinline__ void gemm_phase(PG8_LAS unsigned char* lds, const Gemm g, const Sched& S, const Epi& E) {
;     ...
;             PG8_WAIT_V(8); PG8_WAIT_L(0); PG8_BAR; PG8_MMA(1, 0, At, B0); PG8_MMA(1, 1, At, B1); PG8_BAR; PG8_SCHED;
;             PG8_LDB(B0, 1, 0); PG8_LDB(B1, 1, 1); PG8_SCHED; PG8_LDA(At, 1, 0); PG8_STAGE(PG8_SA(0, 1), a2 + hstep, voffA);
;             PG8_WAIT_V(8); PG8_WAIT_L(0); PG8_BAR; PG8_MMA(0, 0, At, B0); PG8_MMA(0, 1, At, B1); PG8_BAR; PG8_SCHED;
	s_setprio 1
	v_mfma_f32_16x16x32_bf16 v[60:63], v[144:147], v[186:189], v[60:63]
	v_mfma_f32_16x16x32_bf16 v[56:59], v[162:165], v[186:189], v[56:59]
	v_mfma_f32_16x16x32_bf16 v[48:51], v[144:147], v[194:197], v[48:51]
	v_mfma_f32_16x16x32_bf16 v[40:43], v[162:165], v[194:197], v[40:43]
	v_mfma_f32_16x16x32_bf16 v[32:35], v[144:147], v[202:205], v[32:35]
	v_mfma_f32_16x16x32_bf16 v[24:27], v[162:165], v[202:205], v[24:27]
	v_mfma_f32_16x16x32_bf16 v[16:19], v[144:147], v[210:213], v[16:19]
	v_mfma_f32_16x16x32_bf16 v[8:11], v[162:165], v[210:213], v[8:11]
	v_mfma_f32_16x16x32_bf16 v[60:63], v[158:161], v[190:193], v[60:63]
	v_mfma_f32_16x16x32_bf16 v[56:59], v[166:169], v[190:193], v[56:59]
	v_mfma_f32_16x16x32_bf16 v[48:51], v[158:161], v[198:201], v[48:51]
	v_mfma_f32_16x16x32_bf16 v[40:43], v[166:169], v[198:201], v[40:43]
	v_mfma_f32_16x16x32_bf16 v[32:35], v[158:161], v[206:209], v[32:35]
	v_mfma_f32_16x16x32_bf16 v[24:27], v[166:169], v[206:209], v[24:27]
	v_mfma_f32_16x16x32_bf16 v[16:19], v[158:161], v[214:217], v[16:19]
	v_mfma_f32_16x16x32_bf16 v[8:11], v[166:169], v[214:217], v[8:11]
	s_setprio 0
	s_setprio 1
	v_mfma_f32_16x16x32_bf16 v[52:55], v[170:173], v[186:189], v[52:55]
	v_mfma_f32_16x16x32_bf16 v[44:47], v[178:181], v[186:189], v[44:47]
	v_mfma_f32_16x16x32_bf16 v[36:39], v[170:173], v[194:197], v[36:39]
	v_mfma_f32_16x16x32_bf16 v[28:31], v[178:181], v[194:197], v[28:31]
	v_mfma_f32_16x16x32_bf16 v[20:23], v[170:173], v[202:205], v[20:23]
	v_mfma_f32_16x16x32_bf16 v[12:15], v[178:181], v[202:205], v[12:15]
	v_mfma_f32_16x16x32_bf16 v[4:7], v[170:173], v[210:213], v[4:7]
	v_mfma_f32_16x16x32_bf16 v[0:3], v[178:181], v[210:213], v[0:3]
	v_mfma_f32_16x16x32_bf16 v[52:55], v[174:177], v[190:193], v[52:55]
	v_mfma_f32_16x16x32_bf16 v[44:47], v[182:185], v[190:193], v[44:47]
	v_mfma_f32_16x16x32_bf16 v[36:39], v[174:177], v[198:201], v[36:39]
	v_mfma_f32_16x16x32_bf16 v[28:31], v[182:185], v[198:201], v[28:31]
	v_mfma_f32_16x16x32_bf16 v[20:23], v[174:177], v[206:209], v[20:23]
	v_mfma_f32_16x16x32_bf16 v[12:15], v[182:185], v[206:209], v[12:15]
	v_mfma_f32_16x16x32_bf16 v[4:7], v[174:177], v[214:217], v[4:7]
	v_mfma_f32_16x16x32_bf16 v[0:3], v[182:185], v[214:217], v[0:3]
	s_setprio 0
	s_barrier
	s_add_i32 s51, 0, 0x18000
	v_add_u32_e32 v148, s51, v151
	s_add_i32 s52, 0, 0x1c000
	ds_read_b128 v[144:147], v148
	ds_read_b128 v[158:161], v148 offset:1024
	ds_read_b128 v[162:165], v148 offset:2048
	ds_read_b128 v[166:169], v148 offset:3072
	v_add_u32_e32 v148, s52, v151
	ds_read_b128 v[170:173], v148
	ds_read_b128 v[174:177], v148 offset:1024
	ds_read_b128 v[178:181], v148 offset:2048
	ds_read_b128 v[182:185], v148 offset:3072
	s_add_u32 s28, s28, 0x40000
	s_addc_u32 s29, s29, 0
	s_mov_b32 m0, s35
	v_lshl_add_u64 v[226:227], s[28:29], 0, v[134:135]
	ds_read_b128 v[186:189], v157 offset:32768
	ds_read_b128 v[190:193], v157 offset:33792
	ds_read_b128 v[194:197], v157 offset:34816
	ds_read_b128 v[198:201], v157 offset:35840
	ds_read_b128 v[202:205], v157 offset:36864
	ds_read_b128 v[206:209], v157 offset:37888
	ds_read_b128 v[210:213], v157 offset:38912
	ds_read_b128 v[214:217], v157 offset:39936
	global_load_lds_dwordx4 v[226:227], off
	v_lshl_add_u64 v[226:227], s[28:29], 0, v[130:131]
	s_mov_b32 m0, s36
	s_nop 0
	global_load_lds_dwordx4 v[226:227], off
	s_waitcnt vmcnt(8)
	s_waitcnt lgkmcnt(0)
	s_barrier
	s_setprio 1
	v_mfma_f32_16x16x32_bf16 v[124:127], v[144:147], v[186:189], v[124:127]
	v_mfma_f32_16x16x32_bf16 v[120:123], v[162:165], v[186:189], v[120:123]
	v_mfma_f32_16x16x32_bf16 v[116:119], v[144:147], v[194:197], v[116:119]
	v_mfma_f32_16x16x32_bf16 v[112:115], v[162:165], v[194:197], v[112:115]
	v_mfma_f32_16x16x32_bf16 v[104:107], v[144:147], v[202:205], v[104:107]
	v_mfma_f32_16x16x32_bf16 v[96:99], v[162:165], v[202:205], v[96:99]
	v_mfma_f32_16x16x32_bf16 v[76:79], v[144:147], v[210:213], v[76:79]
	v_mfma_f32_16x16x32_bf16 v[72:75], v[162:165], v[210:213], v[72:75]
	v_mfma_f32_16x16x32_bf16 v[124:127], v[158:161], v[190:193], v[124:127]
	v_mfma_f32_16x16x32_bf16 v[120:123], v[166:169], v[190:193], v[120:123]
	v_mfma_f32_16x16x32_bf16 v[116:119], v[158:161], v[198:201], v[116:119]
	v_mfma_f32_16x16x32_bf16 v[112:115], v[166:169], v[198:201], v[112:115]
	v_mfma_f32_16x16x32_bf16 v[104:107], v[158:161], v[206:209], v[104:107]
	v_mfma_f32_16x16x32_bf16 v[96:99], v[166:169], v[206:209], v[96:99]
	v_mfma_f32_16x16x32_bf16 v[76:79], v[158:161], v[214:217], v[76:79]
	v_mfma_f32_16x16x32_bf16 v[72:75], v[166:169], v[214:217], v[72:75]
	s_setprio 0
	s_setprio 1
	v_mfma_f32_16x16x32_bf16 v[108:111], v[170:173], v[186:189], v[108:111]
	v_mfma_f32_16x16x32_bf16 v[100:103], v[178:181], v[186:189], v[100:103]
	v_mfma_f32_16x16x32_bf16 v[92:95], v[170:173], v[194:197], v[92:95]
	v_mfma_f32_16x16x32_bf16 v[88:91], v[178:181], v[194:197], v[88:91]
	v_mfma_f32_16x16x32_bf16 v[84:87], v[170:173], v[202:205], v[84:87]
	v_mfma_f32_16x16x32_bf16 v[80:83], v[178:181], v[202:205], v[80:83]
	v_mfma_f32_16x16x32_bf16 v[68:71], v[170:173], v[210:213], v[68:71]
	v_mfma_f32_16x16x32_bf16 v[64:67], v[178:181], v[210:213], v[64:67]
	v_mfma_f32_16x16x32_bf16 v[108:111], v[174:177], v[190:193], v[108:111]
	v_mfma_f32_16x16x32_bf16 v[100:103], v[182:185], v[190:193], v[100:103]
	v_mfma_f32_16x16x32_bf16 v[92:95], v[174:177], v[198:201], v[92:95]
	v_mfma_f32_16x16x32_bf16 v[88:91], v[182:185], v[198:201], v[88:91]
	v_mfma_f32_16x16x32_bf16 v[84:87], v[174:177], v[206:209], v[84:87]
	v_mfma_f32_16x16x32_bf16 v[80:83], v[182:185], v[206:209], v[80:83]
	v_mfma_f32_16x16x32_bf16 v[68:71], v[174:177], v[214:217], v[68:71]
	v_mfma_f32_16x16x32_bf16 v[64:67], v[182:185], v[214:217], v[64:67]
	s_setprio 0
	s_barrier
; #define PG8_STAGE(bufoff, gbase, voff) do { _Pragma("unroll") for (int _i = 0; _i < 2; ++_i) \
;         __builtin_amdgcn_global_load_lds((const unsigned*)((const char*)(gbase) + (voff)[_i]), (PG8_LAS unsigned*)(lds + (bufoff) + ldsw + _i * 8192), 16, 0, 0); } while (0)
; #define PG8_LDA(dst, b, h) do { _Pragma("unroll") for (int m = 0; m < 4; ++m) _Pragma("unroll") for (int k = 0; k < 2; ++k) dst[m][k] = *(const PG8_LAS bf16x8*)(lds + PG8_SA(b, h) + aoff + m * 2048 + k * 1024); } while (0)
; #define PG8_MMA(ai, bj, At, Bt) do { __builtin_amdgcn_s_setprio(1); _Pragma("unroll") for (int m = 0; m < 4; ++m) _Pragma("unroll") for (int n = 0; n < 2; ++n) _Pragma("unroll") for (int k = 0; k < 2; ++k) \
;         acc[ai][bj][m][n] = __builtin_amdgcn_mfma_f32_16x16x32_bf16(Bt[n][k], At[m][k], acc[ai][bj][m][n], 0, 0, 0); __builtin_amdgcn_s_setprio(0); } while (0)
; #define PG8_WAIT_V(n) asm volatile("s_waitcnt vmcnt(" #n ")" ::: "memory")
; #define PG8_WAIT_L(n) asm volatile("s_waitcnt lgkmcnt(" #n ")" ::: "memory")
; #define PG8_BAR __builtin_amdgcn_s_barrier()
; #define PG8_SCHED __builtin_amdgcn_sched_barrier(0)
; template <class Epi, class Sched, bool ALIGN_EPI = false, bool SP2 = false>
; __device__ __forceinline__ void gemm_phase(PG8_LAS unsigned char* lds, const Gemm g, const Sched& S, const Epi& E) {
;     ...
;             PG8_LDA(At, 1, 1); PG8_STAGE(PG8_SB(1, 0), b3, voffB); PG8_STAGE(PG8_SB(1, 1), b3 + hstep, voffB); PG8_STAGE(PG8_SA(1, 0), a3, voffA);
;             PG8_WAIT_V(8); PG8_WAIT_L(0); PG8_BAR; PG8_MMA(1, 0, At, B0); PG8_MMA(1, 1, At, B1); PG8_BAR; PG8_SCHED;
;     ...
;         if constexpr (ALIGN_EPI) { if (wr == 0) PG8_BAR; }
	s_add_i32 s28, s51, s30
	v_lshl_add_u64 v[218:219], v[218:219], 0, s[8:9]
	s_mov_b32 m0, s28
	ds_read_b128 v[186:189], v157 offset:49152
	ds_read_b128 v[190:193], v157 offset:50176
	ds_read_b128 v[194:197], v157 offset:51200
	ds_read_b128 v[198:201], v157 offset:52224
	ds_read_b128 v[202:205], v157 offset:53248
	ds_read_b128 v[206:209], v157 offset:54272
	ds_read_b128 v[210:213], v157 offset:55296
	ds_read_b128 v[214:217], v157 offset:56320
	global_load_lds_dwordx4 v[218:219], off
	s_add_i32 m0, s28, 0x2000
	s_add_u32 s26, s26, 0x40080
	v_lshl_add_u64 v[218:219], v[220:221], 0, s[8:9]
	s_addc_u32 s27, s27, 0
	s_add_i32 s28, s52, s30
	global_load_lds_dwordx4 v[218:219], off
	v_lshl_add_u64 v[218:219], s[26:27], 0, v[132:133]
	s_mov_b32 m0, s28
	s_nop 0
	global_load_lds_dwordx4 v[218:219], off
	v_lshl_add_u64 v[218:219], s[26:27], 0, v[128:129]
	s_add_i32 m0, s28, 0x2000
	s_nop 0
	global_load_lds_dwordx4 v[218:219], off
	v_lshl_add_u64 v[218:219], v[222:223], 0, s[8:9]
	s_mov_b32 m0, s38
	s_nop 0
	global_load_lds_dwordx4 v[218:219], off
	v_lshl_add_u64 v[218:219], v[224:225], 0, s[8:9]
	s_mov_b32 m0, s39
	s_nop 0
	global_load_lds_dwordx4 v[218:219], off
	s_waitcnt vmcnt(8)
	s_waitcnt lgkmcnt(0)
	s_barrier
	s_setprio 1
	v_mfma_f32_16x16x32_bf16 v[60:63], v[144:147], v[186:189], v[60:63]
	v_mfma_f32_16x16x32_bf16 v[56:59], v[162:165], v[186:189], v[56:59]
	v_mfma_f32_16x16x32_bf16 v[48:51], v[144:147], v[194:197], v[48:51]
	v_mfma_f32_16x16x32_bf16 v[40:43], v[162:165], v[194:197], v[40:43]
	v_mfma_f32_16x16x32_bf16 v[32:35], v[144:147], v[202:205], v[32:35]
	v_mfma_f32_16x16x32_bf16 v[24:27], v[162:165], v[202:205], v[24:27]
	v_mfma_f32_16x16x32_bf16 v[16:19], v[144:147], v[210:213], v[16:19]
	v_mfma_f32_16x16x32_bf16 v[8:11], v[162:165], v[210:213], v[8:11]
	v_mfma_f32_16x16x32_bf16 v[60:63], v[158:161], v[190:193], v[60:63]
	v_mfma_f32_16x16x32_bf16 v[56:59], v[166:169], v[190:193], v[56:59]
	v_mfma_f32_16x16x32_bf16 v[48:51], v[158:161], v[198:201], v[48:51]
	v_mfma_f32_16x16x32_bf16 v[40:43], v[166:169], v[198:201], v[40:43]
	v_mfma_f32_16x16x32_bf16 v[32:35], v[158:161], v[206:209], v[32:35]
	v_mfma_f32_16x16x32_bf16 v[24:27], v[166:169], v[206:209], v[24:27]
	v_mfma_f32_16x16x32_bf16 v[16:19], v[158:161], v[214:217], v[16:19]
	v_mfma_f32_16x16x32_bf16 v[8:11], v[166:169], v[214:217], v[8:11]
	s_setprio 0
	s_setprio 1
	v_mfma_f32_16x16x32_bf16 v[52:55], v[170:173], v[186:189], v[52:55]
	v_mfma_f32_16x16x32_bf16 v[44:47], v[178:181], v[186:189], v[44:47]
	v_mfma_f32_16x16x32_bf16 v[36:39], v[170:173], v[194:197], v[36:39]
	v_mfma_f32_16x16x32_bf16 v[28:31], v[178:181], v[194:197], v[28:31]
	v_mfma_f32_16x16x32_bf16 v[20:23], v[170:173], v[202:205], v[20:23]
	v_mfma_f32_16x16x32_bf16 v[12:15], v[178:181], v[202:205], v[12:15]
	v_mfma_f32_16x16x32_bf16 v[4:7], v[170:173], v[210:213], v[4:7]
	v_mfma_f32_16x16x32_bf16 v[0:3], v[178:181], v[210:213], v[0:3]
	v_mfma_f32_16x16x32_bf16 v[52:55], v[174:177], v[190:193], v[52:55]
	v_mfma_f32_16x16x32_bf16 v[44:47], v[182:185], v[190:193], v[44:47]
	v_mfma_f32_16x16x32_bf16 v[36:39], v[174:177], v[198:201], v[36:39]
	v_mfma_f32_16x16x32_bf16 v[28:31], v[182:185], v[198:201], v[28:31]
	v_mfma_f32_16x16x32_bf16 v[20:23], v[174:177], v[206:209], v[20:23]
	v_mfma_f32_16x16x32_bf16 v[12:15], v[182:185], v[206:209], v[12:15]
	v_mfma_f32_16x16x32_bf16 v[4:7], v[174:177], v[214:217], v[4:7]
	v_mfma_f32_16x16x32_bf16 v[0:3], v[182:185], v[214:217], v[0:3]
	s_setprio 0
	s_barrier
	s_add_i32 s50, s50, 2
	s_add_u32 s24, s24, 0x100
	s_addc_u32 s25, s25, 0
	s_add_u32 s48, s48, 0x100
	s_addc_u32 s49, s49, 0
	s_cmp_gt_u32 s50, 13
	s_cbranch_scc0 .LBB0_67
	s_and_b64 vcc, exec, s[10:11]
	s_cbranch_vccz .LBB0_70
	s_barrier

; #define PG8_STAGE(bufoff, gbase, voff) do { _Pragma("unroll") for (int _i = 0; _i < 2; ++_i) \
;         __builtin_amdgcn_global_load_lds((const unsigned*)((const char*)(gbase) + (voff)[_i]), (PG8_LAS unsigned*)(lds + (bufoff) + ldsw + _i * 8192), 16, 0, 0); } while (0)
; #define PG8_LDA(dst, b, h) do { _Pragma("unroll") for (int m = 0; m < 4; ++m) _Pragma("unroll") for (int k = 0; k < 2; ++k) dst[m][k] = *(const PG8_LAS bf16x8*)(lds + PG8_SA(b, h) + aoff + m * 2048 + k * 1024); } while (0)
; #define PG8_LDB(dst, b, h) do { _Pragma("unroll") for (int n = 0; n < 2; ++n) _Pragma("unroll") for (int k = 0; k < 2; ++k) dst[n][k] = *(const PG8_LAS bf16x8*)(lds + PG8_SB(b, h) + boff + n * 2048 + k * 1024); } while (0)
; #define PG8_MMA(ai, bj, At, Bt) do { __builtin_amdgcn_s_setprio(1); _Pragma("unroll") for (int m = 0; m < 4; ++m) _Pragma("unroll") for (int n = 0; n < 2; ++n) _Pragma("unroll") for (int k = 0; k < 2; ++k) \
;         acc[ai][bj][m][n] = __builtin_amdgcn_mfma_f32_16x16x32_bf16(Bt[n][k], At[m][k], acc[ai][bj][m][n], 0, 0, 0); __builtin_amdgcn_s_setprio(0); } while (0)
; #define PG8_WAIT_V(n) asm volatile("s_waitcnt vmcnt(" #n ")" ::: "memory")
; #define PG8_WAIT_L(n) asm volatile("s_waitcnt lgkmcnt(" #n ")" ::: "memory")
; #define PG8_BAR __builtin_amdgcn_s_barrier()
; #define PG8_SCHED __builtin_amdgcn_sched_barrier(0)
; template <class Epi, class Sched, bool ALIGN_EPI = false, bool SP2 = false>
; __device__ __forceinline__ void gemm_phase(PG8_LAS unsigned char* lds, const Gemm g, const Sched& S, const Epi& E) {
;     ...
;             PG8_LDB(B0, 0, 0); PG8_LDB(B1, 0, 1); PG8_SCHED; PG8_LDA(At, 0, 0); PG8_STAGE(PG8_SA(1, 1), a1 + hstep, voffA);
;             PG8_WAIT_V(8); PG8_WAIT_L(0); PG8_BAR; PG8_MMA(0, 0, At, B0); PG8_MMA(0, 1, At, B1); PG8_BAR; PG8_SCHED;
;             PG8_LDA(At, 0, 1); PG8_STAGE(PG8_SB(0, 0), b2, voffB); PG8_STAGE(PG8_SB(0, 1), b2 + hstep, voffB); PG8_STAGE(PG8_SA(0, 0), a2, voffA);
;             PG8_WAIT_V(8); PG8_WAIT_L(0); PG8_BAR; PG8_MMA(1, 0, At, B0); PG8_MMA(1, 1, At, B1); PG8_BAR; PG8_SCHED;
.LBB0_660:
	ds_read_b128 v[128:131], v191
	ds_read_b128 v[132:135], v191 offset:1024
	ds_read_b128 v[136:139], v191 offset:2048
	ds_read_b128 v[140:143], v191 offset:3072
	ds_read_b128 v[144:147], v192
	ds_read_b128 v[148:151], v192 offset:1024
	ds_read_b128 v[170:173], v192 offset:2048
	ds_read_b128 v[174:177], v192 offset:3072
	s_add_u32 s40, s38, 0xfffc0080
	s_addc_u32 s41, s39, -1
	s_cmp_eq_u32 s60, 12
	s_cselect_b32 s43, s29, s41
	s_cselect_b32 s42, s37, s40
	s_cselect_b32 s41, s27, s59
	s_cselect_b32 s40, s57, s58
	v_lshl_add_u64 v[186:187], s[38:39], 0, v[162:163]
	s_add_i32 m0, s44, 0xc000
	ds_read_b128 v[178:181], v193
	ds_read_b128 v[182:185], v193 offset:1024
	ds_read_b128 v[196:199], v193 offset:2048
	ds_read_b128 v[200:203], v193 offset:3072
	ds_read_b128 v[204:207], v193 offset:4096
	ds_read_b128 v[208:211], v193 offset:5120
	ds_read_b128 v[212:215], v193 offset:6144
	ds_read_b128 v[216:219], v193 offset:7168
	global_load_lds_dwordx4 v[186:187], off
	v_lshl_add_u64 v[186:187], s[38:39], 0, v[164:165]
	s_add_i32 m0, s44, 0xe000
	s_nop 0
	global_load_lds_dwordx4 v[186:187], off
	s_waitcnt vmcnt(8)
	s_waitcnt lgkmcnt(0)
	s_barrier
	s_setprio 1
	v_mfma_f32_16x16x32_bf16 v[124:127], v[128:131], v[178:181], v[124:127]
	v_mfma_f32_16x16x32_bf16 v[120:123], v[136:139], v[178:181], v[120:123]
	v_mfma_f32_16x16x32_bf16 v[108:111], v[128:131], v[196:199], v[108:111]
	v_mfma_f32_16x16x32_bf16 v[104:107], v[136:139], v[196:199], v[104:107]
	v_mfma_f32_16x16x32_bf16 v[92:95], v[128:131], v[204:207], v[92:95]
	v_mfma_f32_16x16x32_bf16 v[88:91], v[136:139], v[204:207], v[88:91]
	v_mfma_f32_16x16x32_bf16 v[76:79], v[128:131], v[212:215], v[76:79]
	v_mfma_f32_16x16x32_bf16 v[72:75], v[136:139], v[212:215], v[72:75]
	v_mfma_f32_16x16x32_bf16 v[124:127], v[132:135], v[182:185], v[124:127]
	v_mfma_f32_16x16x32_bf16 v[120:123], v[140:143], v[182:185], v[120:123]
	v_mfma_f32_16x16x32_bf16 v[108:111], v[132:135], v[200:203], v[108:111]
	v_mfma_f32_16x16x32_bf16 v[104:107], v[140:143], v[200:203], v[104:107]
	v_mfma_f32_16x16x32_bf16 v[92:95], v[132:135], v[208:211], v[92:95]
	v_mfma_f32_16x16x32_bf16 v[88:91], v[140:143], v[208:211], v[88:91]
	v_mfma_f32_16x16x32_bf16 v[76:79], v[132:135], v[216:219], v[76:79]
	v_mfma_f32_16x16x32_bf16 v[72:75], v[140:143], v[216:219], v[72:75]
	s_setprio 0
	s_setprio 1
	v_mfma_f32_16x16x32_bf16 v[116:119], v[144:147], v[178:181], v[116:119]
	v_mfma_f32_16x16x32_bf16 v[112:115], v[170:173], v[178:181], v[112:115]
	v_mfma_f32_16x16x32_bf16 v[100:103], v[144:147], v[196:199], v[100:103]
	v_mfma_f32_16x16x32_bf16 v[96:99], v[170:173], v[196:199], v[96:99]
	v_mfma_f32_16x16x32_bf16 v[84:87], v[144:147], v[204:207], v[84:87]
	v_mfma_f32_16x16x32_bf16 v[80:83], v[170:173], v[204:207], v[80:83]
	v_mfma_f32_16x16x32_bf16 v[68:71], v[144:147], v[212:215], v[68:71]
	v_mfma_f32_16x16x32_bf16 v[64:67], v[170:173], v[212:215], v[64:67]
	v_mfma_f32_16x16x32_bf16 v[116:119], v[148:151], v[182:185], v[116:119]
	v_mfma_f32_16x16x32_bf16 v[112:115], v[174:177], v[182:185], v[112:115]
	v_mfma_f32_16x16x32_bf16 v[100:103], v[148:151], v[200:203], v[100:103]
	v_mfma_f32_16x16x32_bf16 v[96:99], v[174:177], v[200:203], v[96:99]
	v_mfma_f32_16x16x32_bf16 v[84:87], v[148:151], v[208:211], v[84:87]
	v_mfma_f32_16x16x32_bf16 v[80:83], v[174:177], v[208:211], v[80:83]
	v_mfma_f32_16x16x32_bf16 v[68:71], v[148:151], v[216:219], v[68:71]
	v_mfma_f32_16x16x32_bf16 v[64:67], v[174:177], v[216:219], v[64:67]
	s_setprio 0
	s_barrier
	s_add_i32 s61, s54, s33
	v_lshl_add_u64 v[186:187], s[40:41], 0, v[156:157]
	s_mov_b32 m0, s61
	ds_read_b128 v[178:181], v193 offset:16384
	ds_read_b128 v[182:185], v193 offset:17408
	ds_read_b128 v[196:199], v193 offset:18432
	ds_read_b128 v[200:203], v193 offset:19456
	ds_read_b128 v[204:207], v193 offset:20480
	ds_read_b128 v[208:211], v193 offset:21504
	ds_read_b128 v[212:215], v193 offset:22528
	ds_read_b128 v[216:219], v193 offset:23552
	global_load_lds_dwordx4 v[186:187], off
	s_add_i32 m0, s61, 0x2000
	s_add_u32 s62, s40, 0x40000
	v_lshl_add_u64 v[220:221], s[40:41], 0, v[160:161]
	s_addc_u32 s63, s41, 0
	s_add_i32 s61, s55, s33
	global_load_lds_dwordx4 v[220:221], off
	v_lshl_add_u64 v[222:223], s[62:63], 0, v[156:157]
	s_mov_b32 m0, s61
	v_lshl_add_u64 v[224:225], s[42:43], 0, v[158:159]
	global_load_lds_dwordx4 v[222:223], off
	v_lshl_add_u64 v[222:223], s[62:63], 0, v[160:161]
	s_add_i32 m0, s61, 0x2000
	s_nop 0
	global_load_lds_dwordx4 v[222:223], off
	v_lshl_add_u64 v[222:223], s[42:43], 0, v[154:155]
	s_mov_b32 m0, s44
	s_nop 0
	global_load_lds_dwordx4 v[222:223], off
	s_mov_b32 m0, s45
	s_nop 0
	global_load_lds_dwordx4 v[224:225], off
	s_waitcnt vmcnt(8)
	s_waitcnt lgkmcnt(0)
	s_barrier
; #define PG8_STAGE(bufoff, gbase, voff) do { _Pragma("unroll") for (int _i = 0; _i < 2; ++_i) \
;         __builtin_amdgcn_global_load_lds((const unsigned*)((const char*)(gbase) + (voff)[_i]), (PG8_LAS unsigned*)(lds + (bufoff) + ldsw + _i * 8192), 16, 0, 0); } while (0)
; #define PG8_LDA(dst, b, h) do { _Pragma("unroll") for (int m = 0; m < 4; ++m) _Pragma("unroll") for (int k = 0; k < 2; ++k) dst[m][k] = *(const PG8_LAS bf16x8*)(lds + PG8_SA(b, h) + aoff + m * 2048 + k * 1024); } while (0)
; #define PG8_LDB(dst, b, h) do { _Pragma("unroll") for (int n = 0; n < 2; ++n) _Pragma("unroll") for (int k = 0; k < 2; ++k) dst[n][k] = *(const PG8_LAS bf16x8*)(lds + PG8_SB(b, h) + boff + n * 2048 + k * 1024); } while (0)
; #define PG8_MMA(ai, bj, At, Bt) do { __builtin_amdgcn_s_setprio(1); _Pragma("unroll") for (int m = 0; m < 4; ++m) _Pragma("unroll") for (int n = 0; n < 2; ++n) _Pragma("unroll") for (int k = 0; k < 2; ++k) \
;         acc[ai][bj][m][n] = __builtin_amdgcn_mfma_f32_16x16x32_bf16(Bt[n][k], At[m][k], acc[ai][bj][m][n], 0, 0, 0); __builtin_amdgcn_s_setprio(0); } while (0)
; #define PG8_WAIT_V(n) asm volatile("s_waitcnt vmcnt(" #n ")" ::: "memory")
; #define PG8_WAIT_L(n) asm volatile("s_waitcnt lgkmcnt(" #n ")" ::: "memory")
; #define PG8_BAR __builtin_amdgcn_s_barrier()
; #define PG8_SCHED __builtin_amdgcn_sched_barrier(0)
; template <class Epi, class Sched, bool ALIGN_EPI = false, bool SP2 = false>
; __device__ __forceinline__ void gemm_phase(PG8_LAS unsigned char* lds, const Gemm g, const Sched& S, const Epi& E) {
;     ...
;             PG8_WAIT_V(8); PG8_WAIT_L(0); PG8_BAR; PG8_MMA(1, 0, At, B0); PG8_MMA(1, 1, At, B1); PG8_BAR; PG8_SCHED;
;             PG8_LDB(B0, 1, 0); PG8_LDB(B1, 1, 1); PG8_SCHED; PG8_LDA(At, 1, 0); PG8_STAGE(PG8_SA(0, 1), a2 + hstep, voffA);
;             PG8_WAIT_V(8); PG8_WAIT_L(0); PG8_BAR; PG8_MMA(0, 0, At, B0); PG8_MMA(0, 1, At, B1); PG8_BAR; PG8_SCHED;
	s_setprio 1
	v_mfma_f32_16x16x32_bf16 v[60:63], v[128:131], v[178:181], v[60:63]
	v_mfma_f32_16x16x32_bf16 v[56:59], v[136:139], v[178:181], v[56:59]
	v_mfma_f32_16x16x32_bf16 v[44:47], v[128:131], v[196:199], v[44:47]
	v_mfma_f32_16x16x32_bf16 v[40:43], v[136:139], v[196:199], v[40:43]
	v_mfma_f32_16x16x32_bf16 v[28:31], v[128:131], v[204:207], v[28:31]
	v_mfma_f32_16x16x32_bf16 v[24:27], v[136:139], v[204:207], v[24:27]
	v_mfma_f32_16x16x32_bf16 v[12:15], v[128:131], v[212:215], v[12:15]
	v_mfma_f32_16x16x32_bf16 v[8:11], v[136:139], v[212:215], v[8:11]
	v_mfma_f32_16x16x32_bf16 v[60:63], v[132:135], v[182:185], v[60:63]
	v_mfma_f32_16x16x32_bf16 v[56:59], v[140:143], v[182:185], v[56:59]
	v_mfma_f32_16x16x32_bf16 v[44:47], v[132:135], v[200:203], v[44:47]
	v_mfma_f32_16x16x32_bf16 v[40:43], v[140:143], v[200:203], v[40:43]
	v_mfma_f32_16x16x32_bf16 v[28:31], v[132:135], v[208:211], v[28:31]
	v_mfma_f32_16x16x32_bf16 v[24:27], v[140:143], v[208:211], v[24:27]
	v_mfma_f32_16x16x32_bf16 v[12:15], v[132:135], v[216:219], v[12:15]
	v_mfma_f32_16x16x32_bf16 v[8:11], v[140:143], v[216:219], v[8:11]
	s_setprio 0
	s_setprio 1
	v_mfma_f32_16x16x32_bf16 v[52:55], v[144:147], v[178:181], v[52:55]
	v_mfma_f32_16x16x32_bf16 v[48:51], v[170:173], v[178:181], v[48:51]
	v_mfma_f32_16x16x32_bf16 v[36:39], v[144:147], v[196:199], v[36:39]
	v_mfma_f32_16x16x32_bf16 v[32:35], v[170:173], v[196:199], v[32:35]
	v_mfma_f32_16x16x32_bf16 v[20:23], v[144:147], v[204:207], v[20:23]
	v_mfma_f32_16x16x32_bf16 v[16:19], v[170:173], v[204:207], v[16:19]
	v_mfma_f32_16x16x32_bf16 v[4:7], v[144:147], v[212:215], v[4:7]
	v_mfma_f32_16x16x32_bf16 v[0:3], v[170:173], v[212:215], v[0:3]
	v_mfma_f32_16x16x32_bf16 v[52:55], v[148:151], v[182:185], v[52:55]
	v_mfma_f32_16x16x32_bf16 v[48:51], v[174:177], v[182:185], v[48:51]
	v_mfma_f32_16x16x32_bf16 v[36:39], v[148:151], v[200:203], v[36:39]
	v_mfma_f32_16x16x32_bf16 v[32:35], v[174:177], v[200:203], v[32:35]
	v_mfma_f32_16x16x32_bf16 v[20:23], v[148:151], v[208:211], v[20:23]
	v_mfma_f32_16x16x32_bf16 v[16:19], v[174:177], v[208:211], v[16:19]
	v_mfma_f32_16x16x32_bf16 v[4:7], v[148:151], v[216:219], v[4:7]
	v_mfma_f32_16x16x32_bf16 v[0:3], v[174:177], v[216:219], v[0:3]
	s_setprio 0
	s_barrier
	s_add_i32 s61, 0, 0x18000
	s_add_i32 s62, 0, 0x1c000
	v_add_u32_e32 v140, s61, v189
	v_add_u32_e32 v174, s62, v189
	ds_read_b128 v[128:131], v140
	ds_read_b128 v[132:135], v140 offset:1024
	ds_read_b128 v[136:139], v140 offset:2048
	ds_read_b128 v[140:143], v140 offset:3072
	ds_read_b128 v[144:147], v174
	ds_read_b128 v[148:151], v174 offset:1024
	ds_read_b128 v[170:173], v174 offset:2048
	ds_read_b128 v[174:177], v174 offset:3072
	s_add_u32 s42, s42, 0x40000
	s_addc_u32 s43, s43, 0
	s_mov_b32 m0, s46
	v_lshl_add_u64 v[226:227], s[42:43], 0, v[154:155]
	ds_read_b128 v[178:181], v193 offset:32768
	ds_read_b128 v[182:185], v193 offset:33792
	ds_read_b128 v[196:199], v193 offset:34816
	ds_read_b128 v[200:203], v193 offset:35840
	ds_read_b128 v[204:207], v193 offset:36864
	ds_read_b128 v[208:211], v193 offset:37888
	ds_read_b128 v[212:215], v193 offset:38912
	ds_read_b128 v[216:219], v193 offset:39936
	global_load_lds_dwordx4 v[226:227], off
	v_lshl_add_u64 v[226:227], s[42:43], 0, v[158:159]
	s_mov_b32 m0, s47
	s_nop 0
	global_load_lds_dwordx4 v[226:227], off
	s_waitcnt vmcnt(8)
	s_waitcnt lgkmcnt(0)
	s_barrier
	s_setprio 1
	v_mfma_f32_16x16x32_bf16 v[124:127], v[128:131], v[178:181], v[124:127]
	v_mfma_f32_16x16x32_bf16 v[120:123], v[136:139], v[178:181], v[120:123]
	v_mfma_f32_16x16x32_bf16 v[108:111], v[128:131], v[196:199], v[108:111]
	v_mfma_f32_16x16x32_bf16 v[104:107], v[136:139], v[196:199], v[104:107]
	v_mfma_f32_16x16x32_bf16 v[92:95], v[128:131], v[204:207], v[92:95]
	v_mfma_f32_16x16x32_bf16 v[88:91], v[136:139], v[204:207], v[88:91]
	v_mfma_f32_16x16x32_bf16 v[76:79], v[128:131], v[212:215], v[76:79]
	v_mfma_f32_16x16x32_bf16 v[72:75], v[136:139], v[212:215], v[72:75]
	v_mfma_f32_16x16x32_bf16 v[124:127], v[132:135], v[182:185], v[124:127]
	v_mfma_f32_16x16x32_bf16 v[120:123], v[140:143], v[182:185], v[120:123]
	v_mfma_f32_16x16x32_bf16 v[108:111], v[132:135], v[200:203], v[108:111]
	v_mfma_f32_16x16x32_bf16 v[104:107], v[140:143], v[200:203], v[104:107]
	v_mfma_f32_16x16x32_bf16 v[92:95], v[132:135], v[208:211], v[92:95]
	v_mfma_f32_16x16x32_bf16 v[88:91], v[140:143], v[208:211], v[88:91]
	v_mfma_f32_16x16x32_bf16 v[76:79], v[132:135], v[216:219], v[76:79]
	v_mfma_f32_16x16x32_bf16 v[72:75], v[140:143], v[216:219], v[72:75]
	s_setprio 0
	s_setprio 1
	v_mfma_f32_16x16x32_bf16 v[116:119], v[144:147], v[178:181], v[116:119]
	v_mfma_f32_16x16x32_bf16 v[112:115], v[170:173], v[178:181], v[112:115]
	v_mfma_f32_16x16x32_bf16 v[100:103], v[144:147], v[196:199], v[100:103]
	v_mfma_f32_16x16x32_bf16 v[96:99], v[170:173], v[196:199], v[96:99]
	v_mfma_f32_16x16x32_bf16 v[84:87], v[144:147], v[204:207], v[84:87]
	v_mfma_f32_16x16x32_bf16 v[80:83], v[170:173], v[204:207], v[80:83]
	v_mfma_f32_16x16x32_bf16 v[68:71], v[144:147], v[212:215], v[68:71]
	v_mfma_f32_16x16x32_bf16 v[64:67], v[170:173], v[212:215], v[64:67]
	v_mfma_f32_16x16x32_bf16 v[116:119], v[148:151], v[182:185], v[116:119]
	v_mfma_f32_16x16x32_bf16 v[112:115], v[174:177], v[182:185], v[112:115]
	v_mfma_f32_16x16x32_bf16 v[100:103], v[148:151], v[200:203], v[100:103]
	v_mfma_f32_16x16x32_bf16 v[96:99], v[174:177], v[200:203], v[96:99]
	v_mfma_f32_16x16x32_bf16 v[84:87], v[148:151], v[208:211], v[84:87]
	v_mfma_f32_16x16x32_bf16 v[80:83], v[174:177], v[208:211], v[80:83]
	v_mfma_f32_16x16x32_bf16 v[68:71], v[148:151], v[216:219], v[68:71]
	v_mfma_f32_16x16x32_bf16 v[64:67], v[174:177], v[216:219], v[64:67]
	s_setprio 0
	s_barrier
; #define PG8_STAGE(bufoff, gbase, voff) do { _Pragma("unroll") for (int _i = 0; _i < 2; ++_i) \
;         __builtin_amdgcn_global_load_lds((const unsigned*)((const char*)(gbase) + (voff)[_i]), (PG8_LAS unsigned*)(lds + (bufoff) + ldsw + _i * 8192), 16, 0, 0); } while (0)
; #define PG8_LDA(dst, b, h) do { _Pragma("unroll") for (int m = 0; m < 4; ++m) _Pragma("unroll") for (int k = 0; k < 2; ++k) dst[m][k] = *(const PG8_LAS bf16x8*)(lds + PG8_SA(b, h) + aoff + m * 2048 + k * 1024); } while (0)
; #define PG8_MMA(ai, bj, At, Bt) do { __builtin_amdgcn_s_setprio(1); _Pragma("unroll") for (int m = 0; m < 4; ++m) _Pragma("unroll") for (int n = 0; n < 2; ++n) _Pragma("unroll") for (int k = 0; k < 2; ++k) \
;         acc[ai][bj][m][n] = __builtin_amdgcn_mfma_f32_16x16x32_bf16(Bt[n][k], At[m][k], acc[ai][bj][m][n], 0, 0, 0); __builtin_amdgcn_s_setprio(0); } while (0)
; #define PG8_WAIT_V(n) asm volatile("s_waitcnt vmcnt(" #n ")" ::: "memory")
; #define PG8_WAIT_L(n) asm volatile("s_waitcnt lgkmcnt(" #n ")" ::: "memory")
; #define PG8_BAR __builtin_amdgcn_s_barrier()
; #define PG8_SCHED __builtin_amdgcn_sched_barrier(0)
; template <class Epi, class Sched, bool ALIGN_EPI = false, bool SP2 = false>
; __device__ __forceinline__ void gemm_phase(PG8_LAS unsigned char* lds, const Gemm g, const Sched& S, const Epi& E) {
;     ...
;             PG8_LDA(At, 1, 1); PG8_STAGE(PG8_SB(1, 0), b3, voffB); PG8_STAGE(PG8_SB(1, 1), b3 + hstep, voffB); PG8_STAGE(PG8_SA(1, 0), a3, voffA);
;             PG8_WAIT_V(8); PG8_WAIT_L(0); PG8_BAR; PG8_MMA(1, 0, At, B0); PG8_MMA(1, 1, At, B1); PG8_BAR; PG8_SCHED;
;     ...
;         if constexpr (ALIGN_EPI) { if (wr == 0) PG8_BAR; }
	s_add_i32 s42, s61, s33
	v_lshl_add_u64 v[186:187], v[186:187], 0, s[22:23]
	s_mov_b32 m0, s42
	ds_read_b128 v[178:181], v193 offset:49152
	ds_read_b128 v[182:185], v193 offset:50176
	ds_read_b128 v[196:199], v193 offset:51200
	ds_read_b128 v[200:203], v193 offset:52224
	ds_read_b128 v[204:207], v193 offset:53248
	ds_read_b128 v[208:211], v193 offset:54272
	ds_read_b128 v[212:215], v193 offset:55296
	ds_read_b128 v[216:219], v193 offset:56320
	global_load_lds_dwordx4 v[186:187], off
	s_add_i32 m0, s42, 0x2000
	s_add_u32 s40, s40, 0x40080
	v_lshl_add_u64 v[186:187], v[220:221], 0, s[22:23]
	s_addc_u32 s41, s41, 0
	s_add_i32 s42, s62, s33
	global_load_lds_dwordx4 v[186:187], off
	v_lshl_add_u64 v[186:187], s[40:41], 0, v[156:157]
	s_mov_b32 m0, s42
	s_nop 0
	global_load_lds_dwordx4 v[186:187], off
	v_lshl_add_u64 v[186:187], s[40:41], 0, v[160:161]
	s_add_i32 m0, s42, 0x2000
	s_nop 0
	global_load_lds_dwordx4 v[186:187], off
	v_lshl_add_u64 v[186:187], v[222:223], 0, s[22:23]
	s_mov_b32 m0, s49
	s_nop 0
	global_load_lds_dwordx4 v[186:187], off
	v_lshl_add_u64 v[186:187], v[224:225], 0, s[22:23]
	s_mov_b32 m0, s50
	s_nop 0
	global_load_lds_dwordx4 v[186:187], off
	s_waitcnt vmcnt(8)
	s_waitcnt lgkmcnt(0)
	s_barrier
	s_setprio 1
	v_mfma_f32_16x16x32_bf16 v[60:63], v[128:131], v[178:181], v[60:63]
	v_mfma_f32_16x16x32_bf16 v[56:59], v[136:139], v[178:181], v[56:59]
	v_mfma_f32_16x16x32_bf16 v[44:47], v[128:131], v[196:199], v[44:47]
	v_mfma_f32_16x16x32_bf16 v[40:43], v[136:139], v[196:199], v[40:43]
	v_mfma_f32_16x16x32_bf16 v[28:31], v[128:131], v[204:207], v[28:31]
	v_mfma_f32_16x16x32_bf16 v[24:27], v[136:139], v[204:207], v[24:27]
	v_mfma_f32_16x16x32_bf16 v[12:15], v[128:131], v[212:215], v[12:15]
	v_mfma_f32_16x16x32_bf16 v[8:11], v[136:139], v[212:215], v[8:11]
	v_mfma_f32_16x16x32_bf16 v[60:63], v[132:135], v[182:185], v[60:63]
	v_mfma_f32_16x16x32_bf16 v[56:59], v[140:143], v[182:185], v[56:59]
	v_mfma_f32_16x16x32_bf16 v[44:47], v[132:135], v[200:203], v[44:47]
	v_mfma_f32_16x16x32_bf16 v[40:43], v[140:143], v[200:203], v[40:43]
	v_mfma_f32_16x16x32_bf16 v[28:31], v[132:135], v[208:211], v[28:31]
	v_mfma_f32_16x16x32_bf16 v[24:27], v[140:143], v[208:211], v[24:27]
	v_mfma_f32_16x16x32_bf16 v[12:15], v[132:135], v[216:219], v[12:15]
	v_mfma_f32_16x16x32_bf16 v[8:11], v[140:143], v[216:219], v[8:11]
	s_setprio 0
	s_setprio 1
	v_mfma_f32_16x16x32_bf16 v[52:55], v[144:147], v[178:181], v[52:55]
	v_mfma_f32_16x16x32_bf16 v[48:51], v[170:173], v[178:181], v[48:51]
	v_mfma_f32_16x16x32_bf16 v[36:39], v[144:147], v[196:199], v[36:39]
	v_mfma_f32_16x16x32_bf16 v[32:35], v[170:173], v[196:199], v[32:35]
	v_mfma_f32_16x16x32_bf16 v[20:23], v[144:147], v[204:207], v[20:23]
	v_mfma_f32_16x16x32_bf16 v[16:19], v[170:173], v[204:207], v[16:19]
	v_mfma_f32_16x16x32_bf16 v[4:7], v[144:147], v[212:215], v[4:7]
	v_mfma_f32_16x16x32_bf16 v[0:3], v[170:173], v[212:215], v[0:3]
	v_mfma_f32_16x16x32_bf16 v[52:55], v[148:151], v[182:185], v[52:55]
	v_mfma_f32_16x16x32_bf16 v[48:51], v[174:177], v[182:185], v[48:51]
	v_mfma_f32_16x16x32_bf16 v[36:39], v[148:151], v[200:203], v[36:39]
	v_mfma_f32_16x16x32_bf16 v[32:35], v[174:177], v[200:203], v[32:35]
	v_mfma_f32_16x16x32_bf16 v[20:23], v[148:151], v[208:211], v[20:23]
	v_mfma_f32_16x16x32_bf16 v[16:19], v[174:177], v[208:211], v[16:19]
	v_mfma_f32_16x16x32_bf16 v[4:7], v[148:151], v[216:219], v[4:7]
	v_mfma_f32_16x16x32_bf16 v[0:3], v[174:177], v[216:219], v[0:3]
	s_setprio 0
	s_barrier
	s_add_i32 s60, s60, 2
	s_add_u32 s38, s38, 0x100
	s_addc_u32 s39, s39, 0
	s_add_u32 s58, s58, 0x100
	s_addc_u32 s59, s59, 0
	s_cmp_gt_u32 s60, 13
	s_cbranch_scc0 .LBB0_660
	s_and_b64 vcc, exec, s[24:25]
	s_cbranch_vccz .LBB0_663
	s_barrier

; #define PG8_STAGE(bufoff, gbase, voff) do { _Pragma("unroll") for (int _i = 0; _i < 2; ++_i) \
;         __builtin_amdgcn_global_load_lds((const unsigned*)((const char*)(gbase) + (voff)[_i]), (PG8_LAS unsigned*)(lds + (bufoff) + ldsw + _i * 8192), 16, 0, 0); } while (0)
; #define PG8_LDA(dst, b, h) do { _Pragma("unroll") for (int m = 0; m < 4; ++m) _Pragma("unroll") for (int k = 0; k < 2; ++k) dst[m][k] = *(const PG8_LAS bf16x8*)(lds + PG8_SA(b, h) + aoff + m * 2048 + k * 1024); } while (0)
; #define PG8_LDB(dst, b, h) do { _Pragma("unroll") for (int n = 0; n < 2; ++n) _Pragma("unroll") for (int k = 0; k < 2; ++k) dst[n][k] = *(const PG8_LAS bf16x8*)(lds + PG8_SB(b, h) + boff + n * 2048 + k * 1024); } while (0)
; #define PG8_MMA(ai, bj, At, Bt) do { __builtin_amdgcn_s_setprio(1); _Pragma("unroll") for (int m = 0; m < 4; ++m) _Pragma("unroll") for (int n = 0; n < 2; ++n) _Pragma("unroll") for (int k = 0; k < 2; ++k) \
;         acc[ai][bj][m][n] = __builtin_amdgcn_mfma_f32_16x16x32_bf16(Bt[n][k], At[m][k], acc[ai][bj][m][n], 0, 0, 0); __builtin_amdgcn_s_setprio(0); } while (0)
; #define PG8_WAIT_V(n) asm volatile("s_waitcnt vmcnt(" #n ")" ::: "memory")
; #define PG8_WAIT_L(n) asm volatile("s_waitcnt lgkmcnt(" #n ")" ::: "memory")
; #define PG8_BAR __builtin_amdgcn_s_barrier()
; #define PG8_SCHED __builtin_amdgcn_sched_barrier(0)
; template <class Epi, class Sched, bool ALIGN_EPI = false, bool SP2 = false>
; __device__ __forceinline__ void gemm_phase(PG8_LAS unsigned char* lds, const Gemm g, const Sched& S, const Epi& E) {
;     ...
;             PG8_LDB(B0, 0, 0); PG8_LDB(B1, 0, 1); PG8_SCHED; PG8_LDA(At, 0, 0); PG8_STAGE(PG8_SA(1, 1), a1 + hstep, voffA);
;             PG8_WAIT_V(8); PG8_WAIT_L(0); PG8_BAR; PG8_MMA(0, 0, At, B0); PG8_MMA(0, 1, At, B1); PG8_BAR; PG8_SCHED;
;             PG8_LDA(At, 0, 1); PG8_STAGE(PG8_SB(0, 0), b2, voffB); PG8_STAGE(PG8_SB(0, 1), b2 + hstep, voffB); PG8_STAGE(PG8_SA(0, 0), a2, voffA);
;             PG8_WAIT_V(8); PG8_WAIT_L(0); PG8_BAR; PG8_MMA(1, 0, At, B0); PG8_MMA(1, 1, At, B1); PG8_BAR; PG8_SCHED;
.LBB0_745:
	ds_read_b128 v[148:151], v190
	ds_read_b128 v[154:157], v190 offset:1024
	ds_read_b128 v[158:161], v190 offset:2048
	ds_read_b128 v[162:165], v190 offset:3072
	ds_read_b128 v[172:175], v191
	ds_read_b128 v[176:179], v191 offset:1024
	ds_read_b128 v[180:183], v191 offset:2048
	ds_read_b128 v[196:199], v191 offset:3072
	s_add_u32 s10, s8, 0x100
	s_addc_u32 s11, s9, 0
	s_cmp_eq_u32 s71, 12
	s_cselect_b32 s49, s43, s11
	s_cselect_b32 s48, s67, s10
	s_cselect_b32 s13, s41, s70
	s_cselect_b32 s12, s68, s69
	v_lshl_add_u64 v[166:167], s[8:9], 0, v[140:141]
	s_add_i32 m0, s35, 0xc000
	ds_read_b128 v[200:203], v192
	ds_read_b128 v[204:207], v192 offset:1024
	ds_read_b128 v[208:211], v192 offset:2048
	ds_read_b128 v[212:215], v192 offset:3072
	ds_read_b128 v[216:219], v192 offset:4096
	ds_read_b128 v[220:223], v192 offset:5120
	ds_read_b128 v[224:227], v192 offset:6144
	ds_read_b128 v[228:231], v192 offset:7168
	global_load_lds_dwordx4 v[166:167], off
	v_lshl_add_u64 v[166:167], s[8:9], 0, v[142:143]
	s_add_i32 m0, s35, 0xe000
	s_nop 0
	global_load_lds_dwordx4 v[166:167], off
	s_waitcnt vmcnt(8)
	s_waitcnt lgkmcnt(0)
	s_barrier
	s_setprio 1
	v_mfma_f32_16x16x32_bf16 v[124:127], v[148:151], v[200:203], v[124:127]
	v_mfma_f32_16x16x32_bf16 v[92:95], v[158:161], v[200:203], v[92:95]
	v_mfma_f32_16x16x32_bf16 v[120:123], v[148:151], v[208:211], v[120:123]
	v_mfma_f32_16x16x32_bf16 v[80:83], v[158:161], v[208:211], v[80:83]
	v_mfma_f32_16x16x32_bf16 v[116:119], v[148:151], v[216:219], v[116:119]
	v_mfma_f32_16x16x32_bf16 v[88:91], v[158:161], v[216:219], v[88:91]
	v_mfma_f32_16x16x32_bf16 v[112:115], v[148:151], v[224:227], v[112:115]
	v_mfma_f32_16x16x32_bf16 v[84:87], v[158:161], v[224:227], v[84:87]
	v_mfma_f32_16x16x32_bf16 v[124:127], v[154:157], v[204:207], v[124:127]
	v_mfma_f32_16x16x32_bf16 v[92:95], v[162:165], v[204:207], v[92:95]
	v_mfma_f32_16x16x32_bf16 v[120:123], v[154:157], v[212:215], v[120:123]
	v_mfma_f32_16x16x32_bf16 v[80:83], v[162:165], v[212:215], v[80:83]
	v_mfma_f32_16x16x32_bf16 v[116:119], v[154:157], v[220:223], v[116:119]
	v_mfma_f32_16x16x32_bf16 v[88:91], v[162:165], v[220:223], v[88:91]
	v_mfma_f32_16x16x32_bf16 v[112:115], v[154:157], v[228:231], v[112:115]
	v_mfma_f32_16x16x32_bf16 v[84:87], v[162:165], v[228:231], v[84:87]
	s_setprio 0
	s_setprio 1
	v_mfma_f32_16x16x32_bf16 v[108:111], v[172:175], v[200:203], v[108:111]
	v_mfma_f32_16x16x32_bf16 v[64:67], v[180:183], v[200:203], v[64:67]
	v_mfma_f32_16x16x32_bf16 v[104:107], v[172:175], v[208:211], v[104:107]
	v_mfma_f32_16x16x32_bf16 v[68:71], v[180:183], v[208:211], v[68:71]
	v_mfma_f32_16x16x32_bf16 v[100:103], v[172:175], v[216:219], v[100:103]
	v_mfma_f32_16x16x32_bf16 v[72:75], v[180:183], v[216:219], v[72:75]
	v_mfma_f32_16x16x32_bf16 v[96:99], v[172:175], v[224:227], v[96:99]
	v_mfma_f32_16x16x32_bf16 v[76:79], v[180:183], v[224:227], v[76:79]
	v_mfma_f32_16x16x32_bf16 v[108:111], v[176:179], v[204:207], v[108:111]
	v_mfma_f32_16x16x32_bf16 v[64:67], v[196:199], v[204:207], v[64:67]
	v_mfma_f32_16x16x32_bf16 v[104:107], v[176:179], v[212:215], v[104:107]
	v_mfma_f32_16x16x32_bf16 v[68:71], v[196:199], v[212:215], v[68:71]
	v_mfma_f32_16x16x32_bf16 v[100:103], v[176:179], v[220:223], v[100:103]
	v_mfma_f32_16x16x32_bf16 v[72:75], v[196:199], v[220:223], v[72:75]
	v_mfma_f32_16x16x32_bf16 v[96:99], v[176:179], v[228:231], v[96:99]
	v_mfma_f32_16x16x32_bf16 v[76:79], v[196:199], v[228:231], v[76:79]
	s_setprio 0
	s_barrier
	s_add_i32 s8, s61, s33
	v_lshl_add_u64 v[166:167], s[12:13], 0, v[132:133]
	s_mov_b32 m0, s8
	ds_read_b128 v[200:203], v192 offset:16384
	ds_read_b128 v[204:207], v192 offset:17408
	ds_read_b128 v[208:211], v192 offset:18432
	ds_read_b128 v[212:215], v192 offset:19456
	ds_read_b128 v[216:219], v192 offset:20480
	ds_read_b128 v[220:223], v192 offset:21504
	ds_read_b128 v[224:227], v192 offset:22528
	ds_read_b128 v[228:231], v192 offset:23552
	global_load_lds_dwordx4 v[166:167], off
	s_add_i32 m0, s8, 0x2000
	s_add_u32 s8, s12, 0x40000
	v_lshl_add_u64 v[184:185], s[12:13], 0, v[128:129]
	s_addc_u32 s9, s13, 0
	s_add_i32 s72, s62, s33
	global_load_lds_dwordx4 v[184:185], off
	v_lshl_add_u64 v[232:233], s[8:9], 0, v[132:133]
	s_mov_b32 m0, s72
	v_lshl_add_u64 v[234:235], s[48:49], 0, v[130:131]
	global_load_lds_dwordx4 v[232:233], off
	v_lshl_add_u64 v[232:233], s[8:9], 0, v[128:129]
	s_add_i32 m0, s72, 0x2000
	s_nop 0
	global_load_lds_dwordx4 v[232:233], off
	v_lshl_add_u64 v[232:233], s[48:49], 0, v[134:135]
	s_mov_b32 m0, s35
	s_nop 0
	global_load_lds_dwordx4 v[232:233], off
	s_mov_b32 m0, s74
	s_nop 0
	global_load_lds_dwordx4 v[234:235], off
	s_waitcnt vmcnt(8)
	s_waitcnt lgkmcnt(0)
	s_barrier
; #define PG8_STAGE(bufoff, gbase, voff) do { _Pragma("unroll") for (int _i = 0; _i < 2; ++_i) \
;         __builtin_amdgcn_global_load_lds((const unsigned*)((const char*)(gbase) + (voff)[_i]), (PG8_LAS unsigned*)(lds + (bufoff) + ldsw + _i * 8192), 16, 0, 0); } while (0)
; #define PG8_LDA(dst, b, h) do { _Pragma("unroll") for (int m = 0; m < 4; ++m) _Pragma("unroll") for (int k = 0; k < 2; ++k) dst[m][k] = *(const PG8_LAS bf16x8*)(lds + PG8_SA(b, h) + aoff + m * 2048 + k * 1024); } while (0)
; #define PG8_LDB(dst, b, h) do { _Pragma("unroll") for (int n = 0; n < 2; ++n) _Pragma("unroll") for (int k = 0; k < 2; ++k) dst[n][k] = *(const PG8_LAS bf16x8*)(lds + PG8_SB(b, h) + boff + n * 2048 + k * 1024); } while (0)
; #define PG8_MMA(ai, bj, At, Bt) do { __builtin_amdgcn_s_setprio(1); _Pragma("unroll") for (int m = 0; m < 4; ++m) _Pragma("unroll") for (int n = 0; n < 2; ++n) _Pragma("unroll") for (int k = 0; k < 2; ++k) \
;         acc[ai][bj][m][n] = __builtin_amdgcn_mfma_f32_16x16x32_bf16(Bt[n][k], At[m][k], acc[ai][bj][m][n], 0, 0, 0); __builtin_amdgcn_s_setprio(0); } while (0)
; #define PG8_WAIT_V(n) asm volatile("s_waitcnt vmcnt(" #n ")" ::: "memory")
; #define PG8_WAIT_L(n) asm volatile("s_waitcnt lgkmcnt(" #n ")" ::: "memory")
; #define PG8_BAR __builtin_amdgcn_s_barrier()
; #define PG8_SCHED __builtin_amdgcn_sched_barrier(0)
; template <class Epi, class Sched, bool ALIGN_EPI = false, bool SP2 = false>
; __device__ __forceinline__ void gemm_phase(PG8_LAS unsigned char* lds, const Gemm g, const Sched& S, const Epi& E) {
;     ...
;             PG8_WAIT_V(8); PG8_WAIT_L(0); PG8_BAR; PG8_MMA(1, 0, At, B0); PG8_MMA(1, 1, At, B1); PG8_BAR; PG8_SCHED;
;             PG8_LDB(B0, 1, 0); PG8_LDB(B1, 1, 1); PG8_SCHED; PG8_LDA(At, 1, 0); PG8_STAGE(PG8_SA(0, 1), a2 + hstep, voffA);
;             PG8_WAIT_V(8); PG8_WAIT_L(0); PG8_BAR; PG8_MMA(0, 0, At, B0); PG8_MMA(0, 1, At, B1); PG8_BAR; PG8_SCHED;
	s_setprio 1
	v_mfma_f32_16x16x32_bf16 v[60:63], v[148:151], v[200:203], v[60:63]
	v_mfma_f32_16x16x32_bf16 v[16:19], v[158:161], v[200:203], v[16:19]
	v_mfma_f32_16x16x32_bf16 v[56:59], v[148:151], v[208:211], v[56:59]
	v_mfma_f32_16x16x32_bf16 v[20:23], v[158:161], v[208:211], v[20:23]
	v_mfma_f32_16x16x32_bf16 v[52:55], v[148:151], v[216:219], v[52:55]
	v_mfma_f32_16x16x32_bf16 v[24:27], v[158:161], v[216:219], v[24:27]
	v_mfma_f32_16x16x32_bf16 v[48:51], v[148:151], v[224:227], v[48:51]
	v_mfma_f32_16x16x32_bf16 v[28:31], v[158:161], v[224:227], v[28:31]
	v_mfma_f32_16x16x32_bf16 v[60:63], v[154:157], v[204:207], v[60:63]
	v_mfma_f32_16x16x32_bf16 v[16:19], v[162:165], v[204:207], v[16:19]
	v_mfma_f32_16x16x32_bf16 v[56:59], v[154:157], v[212:215], v[56:59]
	v_mfma_f32_16x16x32_bf16 v[20:23], v[162:165], v[212:215], v[20:23]
	v_mfma_f32_16x16x32_bf16 v[52:55], v[154:157], v[220:223], v[52:55]
	v_mfma_f32_16x16x32_bf16 v[24:27], v[162:165], v[220:223], v[24:27]
	v_mfma_f32_16x16x32_bf16 v[48:51], v[154:157], v[228:231], v[48:51]
	v_mfma_f32_16x16x32_bf16 v[28:31], v[162:165], v[228:231], v[28:31]
	s_setprio 0
	s_setprio 1
	v_mfma_f32_16x16x32_bf16 v[44:47], v[172:175], v[200:203], v[44:47]
	v_mfma_f32_16x16x32_bf16 v[0:3], v[180:183], v[200:203], v[0:3]
	v_mfma_f32_16x16x32_bf16 v[40:43], v[172:175], v[208:211], v[40:43]
	v_mfma_f32_16x16x32_bf16 v[4:7], v[180:183], v[208:211], v[4:7]
	v_mfma_f32_16x16x32_bf16 v[36:39], v[172:175], v[216:219], v[36:39]
	v_mfma_f32_16x16x32_bf16 v[8:11], v[180:183], v[216:219], v[8:11]
	v_mfma_f32_16x16x32_bf16 v[32:35], v[172:175], v[224:227], v[32:35]
	v_mfma_f32_16x16x32_bf16 v[12:15], v[180:183], v[224:227], v[12:15]
	v_mfma_f32_16x16x32_bf16 v[44:47], v[176:179], v[204:207], v[44:47]
	v_mfma_f32_16x16x32_bf16 v[0:3], v[196:199], v[204:207], v[0:3]
	v_mfma_f32_16x16x32_bf16 v[40:43], v[176:179], v[212:215], v[40:43]
	v_mfma_f32_16x16x32_bf16 v[4:7], v[196:199], v[212:215], v[4:7]
	v_mfma_f32_16x16x32_bf16 v[36:39], v[176:179], v[220:223], v[36:39]
	v_mfma_f32_16x16x32_bf16 v[8:11], v[196:199], v[220:223], v[8:11]
	v_mfma_f32_16x16x32_bf16 v[32:35], v[176:179], v[228:231], v[32:35]
	v_mfma_f32_16x16x32_bf16 v[12:15], v[196:199], v[228:231], v[12:15]
	s_setprio 0
	s_barrier
	s_add_i32 s72, 0, 0x18000
	s_add_i32 s73, 0, 0x1c000
	v_add_u32_e32 v162, s72, v171
	v_add_u32_e32 v168, s73, v171
	ds_read_b128 v[148:151], v162
	ds_read_b128 v[154:157], v162 offset:1024
	ds_read_b128 v[158:161], v162 offset:2048
	ds_read_b128 v[162:165], v162 offset:3072
	ds_read_b128 v[172:175], v168
	ds_read_b128 v[176:179], v168 offset:1024
	ds_read_b128 v[180:183], v168 offset:2048
	ds_read_b128 v[196:199], v168 offset:3072
	s_add_u32 s8, s48, 0x40000
	s_addc_u32 s9, s49, 0
	s_mov_b32 m0, s52
	v_lshl_add_u64 v[236:237], s[8:9], 0, v[134:135]
	ds_read_b128 v[200:203], v192 offset:32768
	ds_read_b128 v[204:207], v192 offset:33792
	ds_read_b128 v[208:211], v192 offset:34816
	ds_read_b128 v[212:215], v192 offset:35840
	ds_read_b128 v[216:219], v192 offset:36864
	ds_read_b128 v[220:223], v192 offset:37888
	ds_read_b128 v[224:227], v192 offset:38912
	ds_read_b128 v[228:231], v192 offset:39936
	global_load_lds_dwordx4 v[236:237], off
	v_lshl_add_u64 v[236:237], s[8:9], 0, v[130:131]
	s_mov_b32 m0, s53
	s_nop 0
	global_load_lds_dwordx4 v[236:237], off
	s_waitcnt vmcnt(8)
	s_waitcnt lgkmcnt(0)
	s_barrier
	s_setprio 1
	v_mfma_f32_16x16x32_bf16 v[124:127], v[148:151], v[200:203], v[124:127]
	v_mfma_f32_16x16x32_bf16 v[92:95], v[158:161], v[200:203], v[92:95]
	v_mfma_f32_16x16x32_bf16 v[120:123], v[148:151], v[208:211], v[120:123]
	v_mfma_f32_16x16x32_bf16 v[80:83], v[158:161], v[208:211], v[80:83]
	v_mfma_f32_16x16x32_bf16 v[116:119], v[148:151], v[216:219], v[116:119]
	v_mfma_f32_16x16x32_bf16 v[88:91], v[158:161], v[216:219], v[88:91]
	v_mfma_f32_16x16x32_bf16 v[112:115], v[148:151], v[224:227], v[112:115]
	v_mfma_f32_16x16x32_bf16 v[84:87], v[158:161], v[224:227], v[84:87]
	v_mfma_f32_16x16x32_bf16 v[124:127], v[154:157], v[204:207], v[124:127]
	v_mfma_f32_16x16x32_bf16 v[92:95], v[162:165], v[204:207], v[92:95]
	v_mfma_f32_16x16x32_bf16 v[120:123], v[154:157], v[212:215], v[120:123]
	v_mfma_f32_16x16x32_bf16 v[80:83], v[162:165], v[212:215], v[80:83]
	v_mfma_f32_16x16x32_bf16 v[116:119], v[154:157], v[220:223], v[116:119]
	v_mfma_f32_16x16x32_bf16 v[88:91], v[162:165], v[220:223], v[88:91]
	v_mfma_f32_16x16x32_bf16 v[112:115], v[154:157], v[228:231], v[112:115]
	v_mfma_f32_16x16x32_bf16 v[84:87], v[162:165], v[228:231], v[84:87]
	s_setprio 0
	s_setprio 1
	v_mfma_f32_16x16x32_bf16 v[108:111], v[172:175], v[200:203], v[108:111]
	v_mfma_f32_16x16x32_bf16 v[64:67], v[180:183], v[200:203], v[64:67]
	v_mfma_f32_16x16x32_bf16 v[104:107], v[172:175], v[208:211], v[104:107]
	v_mfma_f32_16x16x32_bf16 v[68:71], v[180:183], v[208:211], v[68:71]
	v_mfma_f32_16x16x32_bf16 v[100:103], v[172:175], v[216:219], v[100:103]
	v_mfma_f32_16x16x32_bf16 v[72:75], v[180:183], v[216:219], v[72:75]
	v_mfma_f32_16x16x32_bf16 v[96:99], v[172:175], v[224:227], v[96:99]
	v_mfma_f32_16x16x32_bf16 v[76:79], v[180:183], v[224:227], v[76:79]
	v_mfma_f32_16x16x32_bf16 v[108:111], v[176:179], v[204:207], v[108:111]
	v_mfma_f32_16x16x32_bf16 v[64:67], v[196:199], v[204:207], v[64:67]
	v_mfma_f32_16x16x32_bf16 v[104:107], v[176:179], v[212:215], v[104:107]
	v_mfma_f32_16x16x32_bf16 v[68:71], v[196:199], v[212:215], v[68:71]
	v_mfma_f32_16x16x32_bf16 v[100:103], v[176:179], v[220:223], v[100:103]
	v_mfma_f32_16x16x32_bf16 v[72:75], v[196:199], v[220:223], v[72:75]
	v_mfma_f32_16x16x32_bf16 v[96:99], v[176:179], v[228:231], v[96:99]
	v_mfma_f32_16x16x32_bf16 v[76:79], v[196:199], v[228:231], v[76:79]
	s_setprio 0
	s_barrier
; #define PG8_STAGE(bufoff, gbase, voff) do { _Pragma("unroll") for (int _i = 0; _i < 2; ++_i) \
;         __builtin_amdgcn_global_load_lds((const unsigned*)((const char*)(gbase) + (voff)[_i]), (PG8_LAS unsigned*)(lds + (bufoff) + ldsw + _i * 8192), 16, 0, 0); } while (0)
; #define PG8_LDA(dst, b, h) do { _Pragma("unroll") for (int m = 0; m < 4; ++m) _Pragma("unroll") for (int k = 0; k < 2; ++k) dst[m][k] = *(const PG8_LAS bf16x8*)(lds + PG8_SA(b, h) + aoff + m * 2048 + k * 1024); } while (0)
; #define PG8_MMA(ai, bj, At, Bt) do { __builtin_amdgcn_s_setprio(1); _Pragma("unroll") for (int m = 0; m < 4; ++m) _Pragma("unroll") for (int n = 0; n < 2; ++n) _Pragma("unroll") for (int k = 0; k < 2; ++k) \
;         acc[ai][bj][m][n] = __builtin_amdgcn_mfma_f32_16x16x32_bf16(Bt[n][k], At[m][k], acc[ai][bj][m][n], 0, 0, 0); __builtin_amdgcn_s_setprio(0); } while (0)
; #define PG8_WAIT_V(n) asm volatile("s_waitcnt vmcnt(" #n ")" ::: "memory")
; #define PG8_WAIT_L(n) asm volatile("s_waitcnt lgkmcnt(" #n ")" ::: "memory")
; #define PG8_BAR __builtin_amdgcn_s_barrier()
; #define PG8_SCHED __builtin_amdgcn_sched_barrier(0)
; template <class Epi, class Sched, bool ALIGN_EPI = false, bool SP2 = false>
; __device__ __forceinline__ void gemm_phase(PG8_LAS unsigned char* lds, const Gemm g, const Sched& S, const Epi& E) {
;     ...
;             PG8_LDA(At, 1, 1); PG8_STAGE(PG8_SB(1, 0), b3, voffB); PG8_STAGE(PG8_SB(1, 1), b3 + hstep, voffB); PG8_STAGE(PG8_SA(1, 0), a3, voffA);
;             PG8_WAIT_V(8); PG8_WAIT_L(0); PG8_BAR; PG8_MMA(1, 0, At, B0); PG8_MMA(1, 1, At, B1); PG8_BAR; PG8_SCHED;
;     ...
;         if constexpr (ALIGN_EPI) { if (wr == 0) PG8_BAR; }
	s_add_i32 s8, s72, s33
	v_lshl_add_u64 v[166:167], v[166:167], 0, s[30:31]
	s_mov_b32 m0, s8
	ds_read_b128 v[200:203], v192 offset:49152
	ds_read_b128 v[204:207], v192 offset:50176
	ds_read_b128 v[208:211], v192 offset:51200
	ds_read_b128 v[212:215], v192 offset:52224
	ds_read_b128 v[216:219], v192 offset:53248
	ds_read_b128 v[220:223], v192 offset:54272
	ds_read_b128 v[224:227], v192 offset:55296
	ds_read_b128 v[228:231], v192 offset:56320
	global_load_lds_dwordx4 v[166:167], off
	s_add_i32 m0, s8, 0x2000
	s_add_u32 s8, s12, 0x40080
	v_lshl_add_u64 v[166:167], v[184:185], 0, s[30:31]
	s_addc_u32 s9, s13, 0
	s_add_i32 s12, s73, s33
	global_load_lds_dwordx4 v[166:167], off
	v_lshl_add_u64 v[166:167], s[8:9], 0, v[132:133]
	s_mov_b32 m0, s12
	s_nop 0
	global_load_lds_dwordx4 v[166:167], off
	v_lshl_add_u64 v[166:167], s[8:9], 0, v[128:129]
	s_add_i32 m0, s12, 0x2000
	s_nop 0
	global_load_lds_dwordx4 v[166:167], off
	v_lshl_add_u64 v[166:167], v[232:233], 0, s[30:31]
	s_mov_b32 m0, s54
	s_nop 0
	global_load_lds_dwordx4 v[166:167], off
	v_lshl_add_u64 v[166:167], v[234:235], 0, s[30:31]
	s_mov_b32 m0, s55
	s_nop 0
	global_load_lds_dwordx4 v[166:167], off
	s_waitcnt vmcnt(8)
	s_waitcnt lgkmcnt(0)
	s_barrier
	s_setprio 1
	v_mfma_f32_16x16x32_bf16 v[60:63], v[148:151], v[200:203], v[60:63]
	v_mfma_f32_16x16x32_bf16 v[16:19], v[158:161], v[200:203], v[16:19]
	v_mfma_f32_16x16x32_bf16 v[56:59], v[148:151], v[208:211], v[56:59]
	v_mfma_f32_16x16x32_bf16 v[20:23], v[158:161], v[208:211], v[20:23]
	v_mfma_f32_16x16x32_bf16 v[52:55], v[148:151], v[216:219], v[52:55]
	v_mfma_f32_16x16x32_bf16 v[24:27], v[158:161], v[216:219], v[24:27]
	v_mfma_f32_16x16x32_bf16 v[48:51], v[148:151], v[224:227], v[48:51]
	v_mfma_f32_16x16x32_bf16 v[28:31], v[158:161], v[224:227], v[28:31]
	v_mfma_f32_16x16x32_bf16 v[60:63], v[154:157], v[204:207], v[60:63]
	v_mfma_f32_16x16x32_bf16 v[16:19], v[162:165], v[204:207], v[16:19]
	v_mfma_f32_16x16x32_bf16 v[56:59], v[154:157], v[212:215], v[56:59]
	v_mfma_f32_16x16x32_bf16 v[20:23], v[162:165], v[212:215], v[20:23]
	v_mfma_f32_16x16x32_bf16 v[52:55], v[154:157], v[220:223], v[52:55]
	v_mfma_f32_16x16x32_bf16 v[24:27], v[162:165], v[220:223], v[24:27]
	v_mfma_f32_16x16x32_bf16 v[48:51], v[154:157], v[228:231], v[48:51]
	v_mfma_f32_16x16x32_bf16 v[28:31], v[162:165], v[228:231], v[28:31]
	s_setprio 0
	s_setprio 1
	v_mfma_f32_16x16x32_bf16 v[44:47], v[172:175], v[200:203], v[44:47]
	v_mfma_f32_16x16x32_bf16 v[0:3], v[180:183], v[200:203], v[0:3]
	v_mfma_f32_16x16x32_bf16 v[40:43], v[172:175], v[208:211], v[40:43]
	v_mfma_f32_16x16x32_bf16 v[4:7], v[180:183], v[208:211], v[4:7]
	v_mfma_f32_16x16x32_bf16 v[36:39], v[172:175], v[216:219], v[36:39]
	v_mfma_f32_16x16x32_bf16 v[8:11], v[180:183], v[216:219], v[8:11]
	v_mfma_f32_16x16x32_bf16 v[32:35], v[172:175], v[224:227], v[32:35]
	v_mfma_f32_16x16x32_bf16 v[12:15], v[180:183], v[224:227], v[12:15]
	v_mfma_f32_16x16x32_bf16 v[44:47], v[176:179], v[204:207], v[44:47]
	v_mfma_f32_16x16x32_bf16 v[0:3], v[196:199], v[204:207], v[0:3]
	v_mfma_f32_16x16x32_bf16 v[40:43], v[176:179], v[212:215], v[40:43]
	v_mfma_f32_16x16x32_bf16 v[4:7], v[196:199], v[212:215], v[4:7]
	v_mfma_f32_16x16x32_bf16 v[36:39], v[176:179], v[220:223], v[36:39]
	v_mfma_f32_16x16x32_bf16 v[8:11], v[196:199], v[220:223], v[8:11]
	v_mfma_f32_16x16x32_bf16 v[32:35], v[176:179], v[228:231], v[32:35]
	v_mfma_f32_16x16x32_bf16 v[12:15], v[196:199], v[228:231], v[12:15]
	s_setprio 0
	s_barrier
	s_add_i32 s71, s71, 2
	s_add_u32 s69, s69, 0x100
	s_addc_u32 s70, s70, 0
	s_cmp_gt_u32 s71, 13
	s_mov_b64 s[8:9], s[10:11]
	s_cbranch_scc0 .LBB0_745
	s_and_b64 vcc, exec, s[84:85]
	s_cbranch_vccz .LBB0_748
	s_barrier

; #define PG8_STAGE(bufoff, gbase, voff) do { _Pragma("unroll") for (int _i = 0; _i < 2; ++_i) \
;         __builtin_amdgcn_global_load_lds((const unsigned*)((const char*)(gbase) + (voff)[_i]), (PG8_LAS unsigned*)(lds + (bufoff) + ldsw + _i * 8192), 16, 0, 0); } while (0)
; #define PG8_LDA(dst, b, h) do { _Pragma("unroll") for (int m = 0; m < 4; ++m) _Pragma("unroll") for (int k = 0; k < 2; ++k) dst[m][k] = *(const PG8_LAS bf16x8*)(lds + PG8_SA(b, h) + aoff + m * 2048 + k * 1024); } while (0)
; #define PG8_LDB(dst, b, h) do { _Pragma("unroll") for (int n = 0; n < 2; ++n) _Pragma("unroll") for (int k = 0; k < 2; ++k) dst[n][k] = *(const PG8_LAS bf16x8*)(lds + PG8_SB(b, h) + boff + n * 2048 + k * 1024); } while (0)
; #define PG8_MMA(ai, bj, At, Bt) do { __builtin_amdgcn_s_setprio(1); _Pragma("unroll") for (int m = 0; m < 4; ++m) _Pragma("unroll") for (int n = 0; n < 2; ++n) _Pragma("unroll") for (int k = 0; k < 2; ++k) \
;         acc[ai][bj][m][n] = __builtin_amdgcn_mfma_f32_16x16x32_bf16(Bt[n][k], At[m][k], acc[ai][bj][m][n], 0, 0, 0); __builtin_amdgcn_s_setprio(0); } while (0)
; #define PG8_WAIT_V(n) asm volatile("s_waitcnt vmcnt(" #n ")" ::: "memory")
; #define PG8_WAIT_L(n) asm volatile("s_waitcnt lgkmcnt(" #n ")" ::: "memory")
; #define PG8_BAR __builtin_amdgcn_s_barrier()
; #define PG8_SCHED __builtin_amdgcn_sched_barrier(0)
; template <class Epi, class Sched, bool ALIGN_EPI = false, bool SP2 = false>
; __device__ __forceinline__ void gemm_phase(PG8_LAS unsigned char* lds, const Gemm g, const Sched& S, const Epi& E) {
;     ...
;             PG8_LDB(B0, 0, 0); PG8_LDB(B1, 0, 1); PG8_SCHED; PG8_LDA(At, 0, 0); PG8_STAGE(PG8_SA(1, 1), a1 + hstep, voffA);
;             PG8_WAIT_V(8); PG8_WAIT_L(0); PG8_BAR; PG8_MMA(0, 0, At, B0); PG8_MMA(0, 1, At, B1); PG8_BAR; PG8_SCHED;
;             PG8_LDA(At, 0, 1); PG8_STAGE(PG8_SB(0, 0), b2, voffB); PG8_STAGE(PG8_SB(0, 1), b2 + hstep, voffB); PG8_STAGE(PG8_SA(0, 0), a2, voffA);
;             PG8_WAIT_V(8); PG8_WAIT_L(0); PG8_BAR; PG8_MMA(1, 0, At, B0); PG8_MMA(1, 1, At, B1); PG8_BAR; PG8_SCHED;
.LBB0_913:
	ds_read_b128 v[128:131], v191
	ds_read_b128 v[132:135], v191 offset:1024
	ds_read_b128 v[136:139], v191 offset:2048
	ds_read_b128 v[140:143], v191 offset:3072
	ds_read_b128 v[144:147], v192
	ds_read_b128 v[148:151], v192 offset:1024
	ds_read_b128 v[170:173], v192 offset:2048
	ds_read_b128 v[174:177], v192 offset:3072
	s_add_u32 s30, s28, 0xfff50080
	s_addc_u32 s31, s29, -1
	s_cmp_eq_u32 s54, 40
	s_cselect_b32 s35, s5, s31
	s_cselect_b32 s34, s4, s30
	s_cselect_b32 s31, s27, s53
	s_cselect_b32 s30, s26, s52
	v_lshl_add_u64 v[186:187], s[28:29], 0, v[162:163]
	s_add_i32 m0, s36, 0xc000
	ds_read_b128 v[178:181], v193
	ds_read_b128 v[182:185], v193 offset:1024
	ds_read_b128 v[196:199], v193 offset:2048
	ds_read_b128 v[200:203], v193 offset:3072
	ds_read_b128 v[204:207], v193 offset:4096
	ds_read_b128 v[208:211], v193 offset:5120
	ds_read_b128 v[212:215], v193 offset:6144
	ds_read_b128 v[216:219], v193 offset:7168
	global_load_lds_dwordx4 v[186:187], off
	v_lshl_add_u64 v[186:187], s[28:29], 0, v[164:165]
	s_add_i32 m0, s36, 0xe000
	s_nop 0
	global_load_lds_dwordx4 v[186:187], off
	s_waitcnt vmcnt(8)
	s_waitcnt lgkmcnt(0)
	s_barrier
	s_setprio 1
	v_mfma_f32_16x16x32_bf16 v[124:127], v[128:131], v[178:181], v[124:127]
	v_mfma_f32_16x16x32_bf16 v[120:123], v[136:139], v[178:181], v[120:123]
	v_mfma_f32_16x16x32_bf16 v[108:111], v[128:131], v[196:199], v[108:111]
	v_mfma_f32_16x16x32_bf16 v[104:107], v[136:139], v[196:199], v[104:107]
	v_mfma_f32_16x16x32_bf16 v[92:95], v[128:131], v[204:207], v[92:95]
	v_mfma_f32_16x16x32_bf16 v[88:91], v[136:139], v[204:207], v[88:91]
	v_mfma_f32_16x16x32_bf16 v[76:79], v[128:131], v[212:215], v[76:79]
	v_mfma_f32_16x16x32_bf16 v[72:75], v[136:139], v[212:215], v[72:75]
	v_mfma_f32_16x16x32_bf16 v[124:127], v[132:135], v[182:185], v[124:127]
	v_mfma_f32_16x16x32_bf16 v[120:123], v[140:143], v[182:185], v[120:123]
	v_mfma_f32_16x16x32_bf16 v[108:111], v[132:135], v[200:203], v[108:111]
	v_mfma_f32_16x16x32_bf16 v[104:107], v[140:143], v[200:203], v[104:107]
	v_mfma_f32_16x16x32_bf16 v[92:95], v[132:135], v[208:211], v[92:95]
	v_mfma_f32_16x16x32_bf16 v[88:91], v[140:143], v[208:211], v[88:91]
	v_mfma_f32_16x16x32_bf16 v[76:79], v[132:135], v[216:219], v[76:79]
	v_mfma_f32_16x16x32_bf16 v[72:75], v[140:143], v[216:219], v[72:75]
	s_setprio 0
	s_setprio 1
	v_mfma_f32_16x16x32_bf16 v[116:119], v[144:147], v[178:181], v[116:119]
	v_mfma_f32_16x16x32_bf16 v[112:115], v[170:173], v[178:181], v[112:115]
	v_mfma_f32_16x16x32_bf16 v[100:103], v[144:147], v[196:199], v[100:103]
	v_mfma_f32_16x16x32_bf16 v[96:99], v[170:173], v[196:199], v[96:99]
	v_mfma_f32_16x16x32_bf16 v[84:87], v[144:147], v[204:207], v[84:87]
	v_mfma_f32_16x16x32_bf16 v[80:83], v[170:173], v[204:207], v[80:83]
	v_mfma_f32_16x16x32_bf16 v[68:71], v[144:147], v[212:215], v[68:71]
	v_mfma_f32_16x16x32_bf16 v[64:67], v[170:173], v[212:215], v[64:67]
	v_mfma_f32_16x16x32_bf16 v[116:119], v[148:151], v[182:185], v[116:119]
	v_mfma_f32_16x16x32_bf16 v[112:115], v[174:177], v[182:185], v[112:115]
	v_mfma_f32_16x16x32_bf16 v[100:103], v[148:151], v[200:203], v[100:103]
	v_mfma_f32_16x16x32_bf16 v[96:99], v[174:177], v[200:203], v[96:99]
	v_mfma_f32_16x16x32_bf16 v[84:87], v[148:151], v[208:211], v[84:87]
	v_mfma_f32_16x16x32_bf16 v[80:83], v[174:177], v[208:211], v[80:83]
	v_mfma_f32_16x16x32_bf16 v[68:71], v[148:151], v[216:219], v[68:71]
	v_mfma_f32_16x16x32_bf16 v[64:67], v[174:177], v[216:219], v[64:67]
	s_setprio 0
	s_barrier
	s_add_i32 s55, s46, s33
	v_lshl_add_u64 v[186:187], s[30:31], 0, v[156:157]
	s_mov_b32 m0, s55
	ds_read_b128 v[178:181], v193 offset:16384
	ds_read_b128 v[182:185], v193 offset:17408
	ds_read_b128 v[196:199], v193 offset:18432
	ds_read_b128 v[200:203], v193 offset:19456
	ds_read_b128 v[204:207], v193 offset:20480
	ds_read_b128 v[208:211], v193 offset:21504
	ds_read_b128 v[212:215], v193 offset:22528
	ds_read_b128 v[216:219], v193 offset:23552
	global_load_lds_dwordx4 v[186:187], off
	s_add_i32 m0, s55, 0x2000
	s_add_u32 s56, s30, 0xb0000
	v_lshl_add_u64 v[220:221], s[30:31], 0, v[160:161]
	s_addc_u32 s57, s31, 0
	s_add_i32 s55, s47, s33
	global_load_lds_dwordx4 v[220:221], off
	v_lshl_add_u64 v[222:223], s[56:57], 0, v[156:157]
	s_mov_b32 m0, s55
	v_lshl_add_u64 v[224:225], s[34:35], 0, v[158:159]
	global_load_lds_dwordx4 v[222:223], off
	v_lshl_add_u64 v[222:223], s[56:57], 0, v[160:161]
	s_add_i32 m0, s55, 0x2000
	s_nop 0
	global_load_lds_dwordx4 v[222:223], off
	v_lshl_add_u64 v[222:223], s[34:35], 0, v[154:155]
	s_mov_b32 m0, s36
	s_nop 0
	global_load_lds_dwordx4 v[222:223], off
	s_mov_b32 m0, s37
	s_nop 0
	global_load_lds_dwordx4 v[224:225], off
	s_waitcnt vmcnt(8)
	s_waitcnt lgkmcnt(0)
	s_barrier
; #define PG8_STAGE(bufoff, gbase, voff) do { _Pragma("unroll") for (int _i = 0; _i < 2; ++_i) \
;         __builtin_amdgcn_global_load_lds((const unsigned*)((const char*)(gbase) + (voff)[_i]), (PG8_LAS unsigned*)(lds + (bufoff) + ldsw + _i * 8192), 16, 0, 0); } while (0)
; #define PG8_LDA(dst, b, h) do { _Pragma("unroll") for (int m = 0; m < 4; ++m) _Pragma("unroll") for (int k = 0; k < 2; ++k) dst[m][k] = *(const PG8_LAS bf16x8*)(lds + PG8_SA(b, h) + aoff + m * 2048 + k * 1024); } while (0)
; #define PG8_LDB(dst, b, h) do { _Pragma("unroll") for (int n = 0; n < 2; ++n) _Pragma("unroll") for (int k = 0; k < 2; ++k) dst[n][k] = *(const PG8_LAS bf16x8*)(lds + PG8_SB(b, h) + boff + n * 2048 + k * 1024); } while (0)
; #define PG8_MMA(ai, bj, At, Bt) do { __builtin_amdgcn_s_setprio(1); _Pragma("unroll") for (int m = 0; m < 4; ++m) _Pragma("unroll") for (int n = 0; n < 2; ++n) _Pragma("unroll") for (int k = 0; k < 2; ++k) \
;         acc[ai][bj][m][n] = __builtin_amdgcn_mfma_f32_16x16x32_bf16(Bt[n][k], At[m][k], acc[ai][bj][m][n], 0, 0, 0); __builtin_amdgcn_s_setprio(0); } while (0)
; #define PG8_WAIT_V(n) asm volatile("s_waitcnt vmcnt(" #n ")" ::: "memory")
; #define PG8_WAIT_L(n) asm volatile("s_waitcnt lgkmcnt(" #n ")" ::: "memory")
; #define PG8_BAR __builtin_amdgcn_s_barrier()
; #define PG8_SCHED __builtin_amdgcn_sched_barrier(0)
; template <class Epi, class Sched, bool ALIGN_EPI = false, bool SP2 = false>
; __device__ __forceinline__ void gemm_phase(PG8_LAS unsigned char* lds, const Gemm g, const Sched& S, const Epi& E) {
;     ...
;             PG8_WAIT_V(8); PG8_WAIT_L(0); PG8_BAR; PG8_MMA(1, 0, At, B0); PG8_MMA(1, 1, At, B1); PG8_BAR; PG8_SCHED;
;             PG8_LDB(B0, 1, 0); PG8_LDB(B1, 1, 1); PG8_SCHED; PG8_LDA(At, 1, 0); PG8_STAGE(PG8_SA(0, 1), a2 + hstep, voffA);
;             PG8_WAIT_V(8); PG8_WAIT_L(0); PG8_BAR; PG8_MMA(0, 0, At, B0); PG8_MMA(0, 1, At, B1); PG8_BAR; PG8_SCHED;
	s_setprio 1
	v_mfma_f32_16x16x32_bf16 v[60:63], v[128:131], v[178:181], v[60:63]
	v_mfma_f32_16x16x32_bf16 v[56:59], v[136:139], v[178:181], v[56:59]
	v_mfma_f32_16x16x32_bf16 v[44:47], v[128:131], v[196:199], v[44:47]
	v_mfma_f32_16x16x32_bf16 v[40:43], v[136:139], v[196:199], v[40:43]
	v_mfma_f32_16x16x32_bf16 v[28:31], v[128:131], v[204:207], v[28:31]
	v_mfma_f32_16x16x32_bf16 v[24:27], v[136:139], v[204:207], v[24:27]
	v_mfma_f32_16x16x32_bf16 v[12:15], v[128:131], v[212:215], v[12:15]
	v_mfma_f32_16x16x32_bf16 v[8:11], v[136:139], v[212:215], v[8:11]
	v_mfma_f32_16x16x32_bf16 v[60:63], v[132:135], v[182:185], v[60:63]
	v_mfma_f32_16x16x32_bf16 v[56:59], v[140:143], v[182:185], v[56:59]
	v_mfma_f32_16x16x32_bf16 v[44:47], v[132:135], v[200:203], v[44:47]
	v_mfma_f32_16x16x32_bf16 v[40:43], v[140:143], v[200:203], v[40:43]
	v_mfma_f32_16x16x32_bf16 v[28:31], v[132:135], v[208:211], v[28:31]
	v_mfma_f32_16x16x32_bf16 v[24:27], v[140:143], v[208:211], v[24:27]
	v_mfma_f32_16x16x32_bf16 v[12:15], v[132:135], v[216:219], v[12:15]
	v_mfma_f32_16x16x32_bf16 v[8:11], v[140:143], v[216:219], v[8:11]
	s_setprio 0
	s_setprio 1
	v_mfma_f32_16x16x32_bf16 v[52:55], v[144:147], v[178:181], v[52:55]
	v_mfma_f32_16x16x32_bf16 v[48:51], v[170:173], v[178:181], v[48:51]
	v_mfma_f32_16x16x32_bf16 v[36:39], v[144:147], v[196:199], v[36:39]
	v_mfma_f32_16x16x32_bf16 v[32:35], v[170:173], v[196:199], v[32:35]
	v_mfma_f32_16x16x32_bf16 v[20:23], v[144:147], v[204:207], v[20:23]
	v_mfma_f32_16x16x32_bf16 v[16:19], v[170:173], v[204:207], v[16:19]
	v_mfma_f32_16x16x32_bf16 v[4:7], v[144:147], v[212:215], v[4:7]
	v_mfma_f32_16x16x32_bf16 v[0:3], v[170:173], v[212:215], v[0:3]
	v_mfma_f32_16x16x32_bf16 v[52:55], v[148:151], v[182:185], v[52:55]
	v_mfma_f32_16x16x32_bf16 v[48:51], v[174:177], v[182:185], v[48:51]
	v_mfma_f32_16x16x32_bf16 v[36:39], v[148:151], v[200:203], v[36:39]
	v_mfma_f32_16x16x32_bf16 v[32:35], v[174:177], v[200:203], v[32:35]
	v_mfma_f32_16x16x32_bf16 v[20:23], v[148:151], v[208:211], v[20:23]
	v_mfma_f32_16x16x32_bf16 v[16:19], v[174:177], v[208:211], v[16:19]
	v_mfma_f32_16x16x32_bf16 v[4:7], v[148:151], v[216:219], v[4:7]
	v_mfma_f32_16x16x32_bf16 v[0:3], v[174:177], v[216:219], v[0:3]
	s_setprio 0
	s_barrier
	s_add_i32 s55, 0, 0x18000
	s_add_i32 s56, 0, 0x1c000
	v_add_u32_e32 v140, s55, v189
	v_add_u32_e32 v174, s56, v189
	ds_read_b128 v[128:131], v140
	ds_read_b128 v[132:135], v140 offset:1024
	ds_read_b128 v[136:139], v140 offset:2048
	ds_read_b128 v[140:143], v140 offset:3072
	ds_read_b128 v[144:147], v174
	ds_read_b128 v[148:151], v174 offset:1024
	ds_read_b128 v[170:173], v174 offset:2048
	ds_read_b128 v[174:177], v174 offset:3072
	s_add_u32 s34, s34, 0xb0000
	s_addc_u32 s35, s35, 0
	s_mov_b32 m0, s38
	v_lshl_add_u64 v[226:227], s[34:35], 0, v[154:155]
	ds_read_b128 v[178:181], v193 offset:32768
	ds_read_b128 v[182:185], v193 offset:33792
	ds_read_b128 v[196:199], v193 offset:34816
	ds_read_b128 v[200:203], v193 offset:35840
	ds_read_b128 v[204:207], v193 offset:36864
	ds_read_b128 v[208:211], v193 offset:37888
	ds_read_b128 v[212:215], v193 offset:38912
	ds_read_b128 v[216:219], v193 offset:39936
	global_load_lds_dwordx4 v[226:227], off
	v_lshl_add_u64 v[226:227], s[34:35], 0, v[158:159]
	s_mov_b32 m0, s39
	s_nop 0
	global_load_lds_dwordx4 v[226:227], off
	s_waitcnt vmcnt(8)
	s_waitcnt lgkmcnt(0)
	s_barrier
	s_setprio 1
	v_mfma_f32_16x16x32_bf16 v[124:127], v[128:131], v[178:181], v[124:127]
	v_mfma_f32_16x16x32_bf16 v[120:123], v[136:139], v[178:181], v[120:123]
	v_mfma_f32_16x16x32_bf16 v[108:111], v[128:131], v[196:199], v[108:111]
	v_mfma_f32_16x16x32_bf16 v[104:107], v[136:139], v[196:199], v[104:107]
	v_mfma_f32_16x16x32_bf16 v[92:95], v[128:131], v[204:207], v[92:95]
	v_mfma_f32_16x16x32_bf16 v[88:91], v[136:139], v[204:207], v[88:91]
	v_mfma_f32_16x16x32_bf16 v[76:79], v[128:131], v[212:215], v[76:79]
	v_mfma_f32_16x16x32_bf16 v[72:75], v[136:139], v[212:215], v[72:75]
	v_mfma_f32_16x16x32_bf16 v[124:127], v[132:135], v[182:185], v[124:127]
	v_mfma_f32_16x16x32_bf16 v[120:123], v[140:143], v[182:185], v[120:123]
	v_mfma_f32_16x16x32_bf16 v[108:111], v[132:135], v[200:203], v[108:111]
	v_mfma_f32_16x16x32_bf16 v[104:107], v[140:143], v[200:203], v[104:107]
	v_mfma_f32_16x16x32_bf16 v[92:95], v[132:135], v[208:211], v[92:95]
	v_mfma_f32_16x16x32_bf16 v[88:91], v[140:143], v[208:211], v[88:91]
	v_mfma_f32_16x16x32_bf16 v[76:79], v[132:135], v[216:219], v[76:79]
	v_mfma_f32_16x16x32_bf16 v[72:75], v[140:143], v[216:219], v[72:75]
	s_setprio 0
	s_setprio 1
	v_mfma_f32_16x16x32_bf16 v[116:119], v[144:147], v[178:181], v[116:119]
	v_mfma_f32_16x16x32_bf16 v[112:115], v[170:173], v[178:181], v[112:115]
	v_mfma_f32_16x16x32_bf16 v[100:103], v[144:147], v[196:199], v[100:103]
	v_mfma_f32_16x16x32_bf16 v[96:99], v[170:173], v[196:199], v[96:99]
	v_mfma_f32_16x16x32_bf16 v[84:87], v[144:147], v[204:207], v[84:87]
	v_mfma_f32_16x16x32_bf16 v[80:83], v[170:173], v[204:207], v[80:83]
	v_mfma_f32_16x16x32_bf16 v[68:71], v[144:147], v[212:215], v[68:71]
	v_mfma_f32_16x16x32_bf16 v[64:67], v[170:173], v[212:215], v[64:67]
	v_mfma_f32_16x16x32_bf16 v[116:119], v[148:151], v[182:185], v[116:119]
	v_mfma_f32_16x16x32_bf16 v[112:115], v[174:177], v[182:185], v[112:115]
	v_mfma_f32_16x16x32_bf16 v[100:103], v[148:151], v[200:203], v[100:103]
	v_mfma_f32_16x16x32_bf16 v[96:99], v[174:177], v[200:203], v[96:99]
	v_mfma_f32_16x16x32_bf16 v[84:87], v[148:151], v[208:211], v[84:87]
	v_mfma_f32_16x16x32_bf16 v[80:83], v[174:177], v[208:211], v[80:83]
	v_mfma_f32_16x16x32_bf16 v[68:71], v[148:151], v[216:219], v[68:71]
	v_mfma_f32_16x16x32_bf16 v[64:67], v[174:177], v[216:219], v[64:67]
	s_setprio 0
	s_barrier
; #define PG8_STAGE(bufoff, gbase, voff) do { _Pragma("unroll") for (int _i = 0; _i < 2; ++_i) \
;         __builtin_amdgcn_global_load_lds((const unsigned*)((const char*)(gbase) + (voff)[_i]), (PG8_LAS unsigned*)(lds + (bufoff) + ldsw + _i * 8192), 16, 0, 0); } while (0)
; #define PG8_LDA(dst, b, h) do { _Pragma("unroll") for (int m = 0; m < 4; ++m) _Pragma("unroll") for (int k = 0; k < 2; ++k) dst[m][k] = *(const PG8_LAS bf16x8*)(lds + PG8_SA(b, h) + aoff + m * 2048 + k * 1024); } while (0)
; #define PG8_MMA(ai, bj, At, Bt) do { __builtin_amdgcn_s_setprio(1); _Pragma("unroll") for (int m = 0; m < 4; ++m) _Pragma("unroll") for (int n = 0; n < 2; ++n) _Pragma("unroll") for (int k = 0; k < 2; ++k) \
;         acc[ai][bj][m][n] = __builtin_amdgcn_mfma_f32_16x16x32_bf16(Bt[n][k], At[m][k], acc[ai][bj][m][n], 0, 0, 0); __builtin_amdgcn_s_setprio(0); } while (0)
; #define PG8_WAIT_V(n) asm volatile("s_waitcnt vmcnt(" #n ")" ::: "memory")
; #define PG8_WAIT_L(n) asm volatile("s_waitcnt lgkmcnt(" #n ")" ::: "memory")
; #define PG8_BAR __builtin_amdgcn_s_barrier()
; #define PG8_SCHED __builtin_amdgcn_sched_barrier(0)
; template <class Epi, class Sched, bool ALIGN_EPI = false, bool SP2 = false>
; __device__ __forceinline__ void gemm_phase(PG8_LAS unsigned char* lds, const Gemm g, const Sched& S, const Epi& E) {
;     ...
;             PG8_LDA(At, 1, 1); PG8_STAGE(PG8_SB(1, 0), b3, voffB); PG8_STAGE(PG8_SB(1, 1), b3 + hstep, voffB); PG8_STAGE(PG8_SA(1, 0), a3, voffA);
;             PG8_WAIT_V(8); PG8_WAIT_L(0); PG8_BAR; PG8_MMA(1, 0, At, B0); PG8_MMA(1, 1, At, B1); PG8_BAR; PG8_SCHED;
;     ...
;         if constexpr (ALIGN_EPI) { if (wr == 0) PG8_BAR; }
	s_add_i32 s34, s55, s33
	v_lshl_add_u64 v[186:187], v[186:187], 0, s[18:19]
	s_mov_b32 m0, s34
	ds_read_b128 v[178:181], v193 offset:49152
	ds_read_b128 v[182:185], v193 offset:50176
	ds_read_b128 v[196:199], v193 offset:51200
	ds_read_b128 v[200:203], v193 offset:52224
	ds_read_b128 v[204:207], v193 offset:53248
	ds_read_b128 v[208:211], v193 offset:54272
	ds_read_b128 v[212:215], v193 offset:55296
	ds_read_b128 v[216:219], v193 offset:56320
	global_load_lds_dwordx4 v[186:187], off
	s_add_i32 m0, s34, 0x2000
	s_add_u32 s30, s30, 0xb0080
	v_lshl_add_u64 v[186:187], v[220:221], 0, s[18:19]
	s_addc_u32 s31, s31, 0
	s_add_i32 s34, s56, s33
	global_load_lds_dwordx4 v[186:187], off
	v_lshl_add_u64 v[186:187], s[30:31], 0, v[156:157]
	s_mov_b32 m0, s34
	s_nop 0
	global_load_lds_dwordx4 v[186:187], off
	v_lshl_add_u64 v[186:187], s[30:31], 0, v[160:161]
	s_add_i32 m0, s34, 0x2000
	s_nop 0
	global_load_lds_dwordx4 v[186:187], off
	v_lshl_add_u64 v[186:187], v[222:223], 0, s[18:19]
	s_mov_b32 m0, s41
	s_nop 0
	global_load_lds_dwordx4 v[186:187], off
	v_lshl_add_u64 v[186:187], v[224:225], 0, s[18:19]
	s_mov_b32 m0, s42
	s_nop 0
	global_load_lds_dwordx4 v[186:187], off
	s_waitcnt vmcnt(8)
	s_waitcnt lgkmcnt(0)
	s_barrier
	s_setprio 1
	v_mfma_f32_16x16x32_bf16 v[60:63], v[128:131], v[178:181], v[60:63]
	v_mfma_f32_16x16x32_bf16 v[56:59], v[136:139], v[178:181], v[56:59]
	v_mfma_f32_16x16x32_bf16 v[44:47], v[128:131], v[196:199], v[44:47]
	v_mfma_f32_16x16x32_bf16 v[40:43], v[136:139], v[196:199], v[40:43]
	v_mfma_f32_16x16x32_bf16 v[28:31], v[128:131], v[204:207], v[28:31]
	v_mfma_f32_16x16x32_bf16 v[24:27], v[136:139], v[204:207], v[24:27]
	v_mfma_f32_16x16x32_bf16 v[12:15], v[128:131], v[212:215], v[12:15]
	v_mfma_f32_16x16x32_bf16 v[8:11], v[136:139], v[212:215], v[8:11]
	v_mfma_f32_16x16x32_bf16 v[60:63], v[132:135], v[182:185], v[60:63]
	v_mfma_f32_16x16x32_bf16 v[56:59], v[140:143], v[182:185], v[56:59]
	v_mfma_f32_16x16x32_bf16 v[44:47], v[132:135], v[200:203], v[44:47]
	v_mfma_f32_16x16x32_bf16 v[40:43], v[140:143], v[200:203], v[40:43]
	v_mfma_f32_16x16x32_bf16 v[28:31], v[132:135], v[208:211], v[28:31]
	v_mfma_f32_16x16x32_bf16 v[24:27], v[140:143], v[208:211], v[24:27]
	v_mfma_f32_16x16x32_bf16 v[12:15], v[132:135], v[216:219], v[12:15]
	v_mfma_f32_16x16x32_bf16 v[8:11], v[140:143], v[216:219], v[8:11]
	s_setprio 0
	s_setprio 1
	v_mfma_f32_16x16x32_bf16 v[52:55], v[144:147], v[178:181], v[52:55]
	v_mfma_f32_16x16x32_bf16 v[48:51], v[170:173], v[178:181], v[48:51]
	v_mfma_f32_16x16x32_bf16 v[36:39], v[144:147], v[196:199], v[36:39]
	v_mfma_f32_16x16x32_bf16 v[32:35], v[170:173], v[196:199], v[32:35]
	v_mfma_f32_16x16x32_bf16 v[20:23], v[144:147], v[204:207], v[20:23]
	v_mfma_f32_16x16x32_bf16 v[16:19], v[170:173], v[204:207], v[16:19]
	v_mfma_f32_16x16x32_bf16 v[4:7], v[144:147], v[212:215], v[4:7]
	v_mfma_f32_16x16x32_bf16 v[0:3], v[170:173], v[212:215], v[0:3]
	v_mfma_f32_16x16x32_bf16 v[52:55], v[148:151], v[182:185], v[52:55]
	v_mfma_f32_16x16x32_bf16 v[48:51], v[174:177], v[182:185], v[48:51]
	v_mfma_f32_16x16x32_bf16 v[36:39], v[148:151], v[200:203], v[36:39]
	v_mfma_f32_16x16x32_bf16 v[32:35], v[174:177], v[200:203], v[32:35]
	v_mfma_f32_16x16x32_bf16 v[20:23], v[148:151], v[208:211], v[20:23]
	v_mfma_f32_16x16x32_bf16 v[16:19], v[174:177], v[208:211], v[16:19]
	v_mfma_f32_16x16x32_bf16 v[4:7], v[148:151], v[216:219], v[4:7]
	v_mfma_f32_16x16x32_bf16 v[0:3], v[174:177], v[216:219], v[0:3]
	s_setprio 0
	s_barrier
	s_add_i32 s54, s54, 2
	s_add_u32 s28, s28, 0x100
	s_addc_u32 s29, s29, 0
	s_add_u32 s52, s52, 0x100
	s_addc_u32 s53, s53, 0
	s_cmp_gt_u32 s54, 41
	s_cbranch_scc0 .LBB0_913
	s_and_b64 vcc, exec, s[24:25]
	s_cbranch_vccz .LBB0_916
	s_barrier
